# v38
# speedup vs baseline: 1.0046x; 1.0043x over previous
.LBB0_321:
	ds_read_b128 v[144:147], v157
	ds_read_b128 v[148:151], v157 offset:1024
	ds_read_b128 v[164:167], v157 offset:2048
	ds_read_b128 v[168:171], v157 offset:3072
	s_add_u32 s4, s8, 0x100
	s_addc_u32 s5, s9, 0
	s_cmp_eq_u32 s60, 2
	s_cselect_b32 s11, s29, s5
	s_cselect_b32 s10, s28, s4
	s_cselect_b32 s7, s31, s37
	s_cselect_b32 s6, s30, s35
	s_add_i32 m0, s46, 0xc000
	ds_read_b128 v[172:175], v158
	ds_read_b128 v[176:179], v158 offset:1024
	ds_read_b128 v[180:183], v158 offset:2048
	ds_read_b128 v[184:187], v158 offset:3072
	ds_read_b128 v[188:191], v158 offset:4096
	ds_read_b128 v[192:195], v158 offset:5120
	ds_read_b128 v[196:199], v158 offset:6144
	ds_read_b128 v[200:203], v158 offset:7168
	global_load_lds_dwordx4 v136, s[8:9]
	s_add_i32 m0, s46, 0xe000
	s_nop 0
	global_load_lds_dwordx4 v138, s[8:9]
	s_waitcnt lgkmcnt(8)
	s_barrier
	s_waitcnt lgkmcnt(0)
	v_mfma_f32_16x16x32_bf16 v[124:127], v[144:147], v[172:175], v[124:127]
	v_mfma_f32_16x16x32_bf16 v[120:123], v[164:167], v[172:175], v[120:123]
	v_mfma_f32_16x16x32_bf16 v[116:119], v[144:147], v[180:183], v[116:119]
	v_mfma_f32_16x16x32_bf16 v[112:115], v[164:167], v[180:183], v[112:115]
	v_mfma_f32_16x16x32_bf16 v[108:111], v[144:147], v[188:191], v[108:111]
	v_mfma_f32_16x16x32_bf16 v[104:107], v[164:167], v[188:191], v[104:107]
	v_mfma_f32_16x16x32_bf16 v[100:103], v[144:147], v[196:199], v[100:103]
	v_mfma_f32_16x16x32_bf16 v[96:99], v[164:167], v[196:199], v[96:99]
	v_mfma_f32_16x16x32_bf16 v[124:127], v[148:151], v[176:179], v[124:127]
	v_mfma_f32_16x16x32_bf16 v[120:123], v[168:171], v[176:179], v[120:123]
	v_mfma_f32_16x16x32_bf16 v[116:119], v[148:151], v[184:187], v[116:119]
	v_mfma_f32_16x16x32_bf16 v[112:115], v[168:171], v[184:187], v[112:115]
	v_mfma_f32_16x16x32_bf16 v[108:111], v[148:151], v[192:195], v[108:111]
	v_mfma_f32_16x16x32_bf16 v[104:107], v[168:171], v[192:195], v[104:107]
	v_mfma_f32_16x16x32_bf16 v[100:103], v[148:151], v[200:203], v[100:103]
	v_mfma_f32_16x16x32_bf16 v[96:99], v[168:171], v[200:203], v[96:99]
	s_barrier
	s_add_i32 s8, s54, s44
	s_add_u32 s98, s6, s26
	s_addc_u32 s99, s7, s27
	s_mov_b32 m0, s8
	ds_read_b128 v[204:207], v159
	ds_read_b128 v[208:211], v159 offset:1024
	ds_read_b128 v[212:215], v159 offset:2048
	ds_read_b128 v[216:219], v159 offset:3072
	global_load_lds_dwordx4 v130, s[6:7]
	s_add_i32 m0, s8, 0x2000
	s_nop 0
	global_load_lds_dwordx4 v134, s[6:7]
	s_barrier
	s_waitcnt lgkmcnt(0)
	v_mfma_f32_16x16x32_bf16 v[60:63], v[204:207], v[172:175], v[60:63]
	v_mfma_f32_16x16x32_bf16 v[56:59], v[212:215], v[172:175], v[56:59]
	v_mfma_f32_16x16x32_bf16 v[52:55], v[204:207], v[180:183], v[52:55]
	v_mfma_f32_16x16x32_bf16 v[48:51], v[212:215], v[180:183], v[48:51]
	v_mfma_f32_16x16x32_bf16 v[44:47], v[204:207], v[188:191], v[44:47]
	v_mfma_f32_16x16x32_bf16 v[40:43], v[212:215], v[188:191], v[40:43]
	v_mfma_f32_16x16x32_bf16 v[36:39], v[204:207], v[196:199], v[36:39]
	v_mfma_f32_16x16x32_bf16 v[32:35], v[212:215], v[196:199], v[32:35]
	v_mfma_f32_16x16x32_bf16 v[60:63], v[208:211], v[176:179], v[60:63]
	v_mfma_f32_16x16x32_bf16 v[56:59], v[216:219], v[176:179], v[56:59]
	v_mfma_f32_16x16x32_bf16 v[52:55], v[208:211], v[184:187], v[52:55]
	v_mfma_f32_16x16x32_bf16 v[48:51], v[216:219], v[184:187], v[48:51]
	v_mfma_f32_16x16x32_bf16 v[44:47], v[208:211], v[192:195], v[44:47]
	v_mfma_f32_16x16x32_bf16 v[40:43], v[216:219], v[192:195], v[40:43]
	v_mfma_f32_16x16x32_bf16 v[36:39], v[208:211], v[200:203], v[36:39]
	v_mfma_f32_16x16x32_bf16 v[32:35], v[216:219], v[200:203], v[32:35]
	s_mov_b32 m0, s46
	s_add_u32 s100, s10, s26
	s_addc_u32 s101, s11, s27
	s_barrier
	ds_read_b128 v[172:175], v158 offset:16384
	ds_read_b128 v[176:179], v158 offset:17408
	ds_read_b128 v[180:183], v158 offset:18432
	ds_read_b128 v[184:187], v158 offset:19456
	ds_read_b128 v[188:191], v158 offset:20480
	ds_read_b128 v[192:195], v158 offset:21504
	ds_read_b128 v[196:199], v158 offset:22528
	ds_read_b128 v[200:203], v158 offset:23552
	global_load_lds_dwordx4 v128, s[10:11]
	s_mov_b32 m0, s47
	s_nop 0
	global_load_lds_dwordx4 v132, s[10:11]
	s_barrier
	s_waitcnt lgkmcnt(0)
	v_mfma_f32_16x16x32_bf16 v[92:95], v[144:147], v[172:175], v[92:95]
	v_mfma_f32_16x16x32_bf16 v[88:91], v[164:167], v[172:175], v[88:91]
	v_mfma_f32_16x16x32_bf16 v[84:87], v[144:147], v[180:183], v[84:87]
	v_mfma_f32_16x16x32_bf16 v[80:83], v[164:167], v[180:183], v[80:83]
	v_mfma_f32_16x16x32_bf16 v[76:79], v[144:147], v[188:191], v[76:79]
	v_mfma_f32_16x16x32_bf16 v[72:75], v[164:167], v[188:191], v[72:75]
	v_mfma_f32_16x16x32_bf16 v[68:71], v[144:147], v[196:199], v[68:71]
	v_mfma_f32_16x16x32_bf16 v[64:67], v[164:167], v[196:199], v[64:67]
	v_mfma_f32_16x16x32_bf16 v[92:95], v[148:151], v[176:179], v[92:95]
	v_mfma_f32_16x16x32_bf16 v[88:91], v[168:171], v[176:179], v[88:91]
	v_mfma_f32_16x16x32_bf16 v[84:87], v[148:151], v[184:187], v[84:87]
	v_mfma_f32_16x16x32_bf16 v[80:83], v[168:171], v[184:187], v[80:83]
	v_mfma_f32_16x16x32_bf16 v[76:79], v[148:151], v[192:195], v[76:79]
	v_mfma_f32_16x16x32_bf16 v[72:75], v[168:171], v[192:195], v[72:75]
	v_mfma_f32_16x16x32_bf16 v[68:71], v[148:151], v[200:203], v[68:71]
	v_mfma_f32_16x16x32_bf16 v[64:67], v[168:171], v[200:203], v[64:67]
	s_barrier
	s_add_u32 s8, s6, 0x18000
	s_addc_u32 s9, s7, 0
	s_add_i32 s61, s55, s44
	s_mov_b32 m0, s61
	s_nop 0
	global_load_lds_dwordx4 v130, s[8:9]
	s_add_i32 m0, s61, 0x2000
	s_nop 0
	global_load_lds_dwordx4 v134, s[8:9]
	s_waitcnt vmcnt(6)
	s_barrier
	v_mfma_f32_16x16x32_bf16 v[28:31], v[204:207], v[172:175], v[28:31]
	v_mfma_f32_16x16x32_bf16 v[24:27], v[212:215], v[172:175], v[24:27]
	v_mfma_f32_16x16x32_bf16 v[20:23], v[204:207], v[180:183], v[20:23]
	v_mfma_f32_16x16x32_bf16 v[16:19], v[212:215], v[180:183], v[16:19]
	v_mfma_f32_16x16x32_bf16 v[12:15], v[204:207], v[188:191], v[12:15]
	v_mfma_f32_16x16x32_bf16 v[8:11], v[212:215], v[188:191], v[8:11]
	v_mfma_f32_16x16x32_bf16 v[4:7], v[204:207], v[196:199], v[4:7]
	v_mfma_f32_16x16x32_bf16 v[0:3], v[212:215], v[196:199], v[0:3]
	v_mfma_f32_16x16x32_bf16 v[28:31], v[208:211], v[176:179], v[28:31]
	v_mfma_f32_16x16x32_bf16 v[24:27], v[216:219], v[176:179], v[24:27]
	v_mfma_f32_16x16x32_bf16 v[20:23], v[208:211], v[184:187], v[20:23]
	v_mfma_f32_16x16x32_bf16 v[16:19], v[216:219], v[184:187], v[16:19]
	v_mfma_f32_16x16x32_bf16 v[12:15], v[208:211], v[192:195], v[12:15]
	v_mfma_f32_16x16x32_bf16 v[8:11], v[216:219], v[192:195], v[8:11]
	v_mfma_f32_16x16x32_bf16 v[4:7], v[208:211], v[200:203], v[4:7]
	v_mfma_f32_16x16x32_bf16 v[0:3], v[216:219], v[200:203], v[0:3]
	s_add_i32 s61, 0, 0x18000
	v_add_u32_e32 v163, s61, v155
	s_barrier
	ds_read_b128 v[144:147], v163
	ds_read_b128 v[148:151], v163 offset:1024
	ds_read_b128 v[164:167], v163 offset:2048
	ds_read_b128 v[168:171], v163 offset:3072
	s_add_u32 s8, s10, 0x18000
	s_addc_u32 s9, s11, 0
	s_mov_b32 m0, s48
	ds_read_b128 v[172:175], v158 offset:32768
	ds_read_b128 v[176:179], v158 offset:33792
	ds_read_b128 v[180:183], v158 offset:34816
	ds_read_b128 v[184:187], v158 offset:35840
	ds_read_b128 v[188:191], v158 offset:36864
	ds_read_b128 v[192:195], v158 offset:37888
	ds_read_b128 v[196:199], v158 offset:38912
	ds_read_b128 v[200:203], v158 offset:39936
	global_load_lds_dwordx4 v128, s[8:9]
	s_mov_b32 m0, s49
	s_nop 0
	global_load_lds_dwordx4 v132, s[8:9]
	s_waitcnt lgkmcnt(8)
	s_barrier
	s_waitcnt lgkmcnt(0)
	v_mfma_f32_16x16x32_bf16 v[124:127], v[144:147], v[172:175], v[124:127]
	v_mfma_f32_16x16x32_bf16 v[120:123], v[164:167], v[172:175], v[120:123]
	v_mfma_f32_16x16x32_bf16 v[116:119], v[144:147], v[180:183], v[116:119]
	v_mfma_f32_16x16x32_bf16 v[112:115], v[164:167], v[180:183], v[112:115]
	v_mfma_f32_16x16x32_bf16 v[108:111], v[144:147], v[188:191], v[108:111]
	v_mfma_f32_16x16x32_bf16 v[104:107], v[164:167], v[188:191], v[104:107]
	v_mfma_f32_16x16x32_bf16 v[100:103], v[144:147], v[196:199], v[100:103]
	v_mfma_f32_16x16x32_bf16 v[96:99], v[164:167], v[196:199], v[96:99]
	v_mfma_f32_16x16x32_bf16 v[124:127], v[148:151], v[176:179], v[124:127]
	v_mfma_f32_16x16x32_bf16 v[120:123], v[168:171], v[176:179], v[120:123]
	v_mfma_f32_16x16x32_bf16 v[116:119], v[148:151], v[184:187], v[116:119]
	v_mfma_f32_16x16x32_bf16 v[112:115], v[168:171], v[184:187], v[112:115]
	v_mfma_f32_16x16x32_bf16 v[108:111], v[148:151], v[192:195], v[108:111]
	v_mfma_f32_16x16x32_bf16 v[104:107], v[168:171], v[192:195], v[104:107]
	v_mfma_f32_16x16x32_bf16 v[100:103], v[148:151], v[200:203], v[100:103]
	v_mfma_f32_16x16x32_bf16 v[96:99], v[168:171], v[200:203], v[96:99]
	s_barrier
	s_add_i32 s8, 0, 0x1c000
	s_add_i32 s9, s61, s44
	v_add_u32_e32 v163, s8, v155
	s_mov_b32 m0, s9
	ds_read_b128 v[204:207], v163
	ds_read_b128 v[208:211], v163 offset:1024
	ds_read_b128 v[212:215], v163 offset:2048
	ds_read_b128 v[216:219], v163 offset:3072
	global_load_lds_dwordx4 v130, s[98:99]
	s_add_i32 m0, s9, 0x2000
	s_nop 0
	global_load_lds_dwordx4 v134, s[98:99]
	s_barrier
	s_waitcnt lgkmcnt(0)
	v_mfma_f32_16x16x32_bf16 v[60:63], v[204:207], v[172:175], v[60:63]
	v_mfma_f32_16x16x32_bf16 v[56:59], v[212:215], v[172:175], v[56:59]
	v_mfma_f32_16x16x32_bf16 v[52:55], v[204:207], v[180:183], v[52:55]
	v_mfma_f32_16x16x32_bf16 v[48:51], v[212:215], v[180:183], v[48:51]
	v_mfma_f32_16x16x32_bf16 v[44:47], v[204:207], v[188:191], v[44:47]
	v_mfma_f32_16x16x32_bf16 v[40:43], v[212:215], v[188:191], v[40:43]
	v_mfma_f32_16x16x32_bf16 v[36:39], v[204:207], v[196:199], v[36:39]
	v_mfma_f32_16x16x32_bf16 v[32:35], v[212:215], v[196:199], v[32:35]
	v_mfma_f32_16x16x32_bf16 v[60:63], v[208:211], v[176:179], v[60:63]
	v_mfma_f32_16x16x32_bf16 v[56:59], v[216:219], v[176:179], v[56:59]
	v_mfma_f32_16x16x32_bf16 v[52:55], v[208:211], v[184:187], v[52:55]
	v_mfma_f32_16x16x32_bf16 v[48:51], v[216:219], v[184:187], v[48:51]
	v_mfma_f32_16x16x32_bf16 v[44:47], v[208:211], v[192:195], v[44:47]
	v_mfma_f32_16x16x32_bf16 v[40:43], v[216:219], v[192:195], v[40:43]
	v_mfma_f32_16x16x32_bf16 v[36:39], v[208:211], v[200:203], v[36:39]
	v_mfma_f32_16x16x32_bf16 v[32:35], v[216:219], v[200:203], v[32:35]
	s_mov_b32 m0, s51
	s_barrier
	ds_read_b128 v[172:175], v158 offset:49152
	ds_read_b128 v[176:179], v158 offset:50176
	ds_read_b128 v[180:183], v158 offset:51200
	ds_read_b128 v[184:187], v158 offset:52224
	ds_read_b128 v[188:191], v158 offset:53248
	ds_read_b128 v[192:195], v158 offset:54272
	ds_read_b128 v[196:199], v158 offset:55296
	ds_read_b128 v[200:203], v158 offset:56320
	global_load_lds_dwordx4 v128, s[100:101]
	s_mov_b32 m0, s52
	s_nop 0
	global_load_lds_dwordx4 v132, s[100:101]
	s_barrier
	s_waitcnt lgkmcnt(0)
	v_mfma_f32_16x16x32_bf16 v[92:95], v[144:147], v[172:175], v[92:95]
	v_mfma_f32_16x16x32_bf16 v[88:91], v[164:167], v[172:175], v[88:91]
	v_mfma_f32_16x16x32_bf16 v[84:87], v[144:147], v[180:183], v[84:87]
	v_mfma_f32_16x16x32_bf16 v[80:83], v[164:167], v[180:183], v[80:83]
	v_mfma_f32_16x16x32_bf16 v[76:79], v[144:147], v[188:191], v[76:79]
	v_mfma_f32_16x16x32_bf16 v[72:75], v[164:167], v[188:191], v[72:75]
	v_mfma_f32_16x16x32_bf16 v[68:71], v[144:147], v[196:199], v[68:71]
	v_mfma_f32_16x16x32_bf16 v[64:67], v[164:167], v[196:199], v[64:67]
	v_mfma_f32_16x16x32_bf16 v[92:95], v[148:151], v[176:179], v[92:95]
	v_mfma_f32_16x16x32_bf16 v[88:91], v[168:171], v[176:179], v[88:91]
	v_mfma_f32_16x16x32_bf16 v[84:87], v[148:151], v[184:187], v[84:87]
	v_mfma_f32_16x16x32_bf16 v[80:83], v[168:171], v[184:187], v[80:83]
	v_mfma_f32_16x16x32_bf16 v[76:79], v[148:151], v[192:195], v[76:79]
	v_mfma_f32_16x16x32_bf16 v[72:75], v[168:171], v[192:195], v[72:75]
	v_mfma_f32_16x16x32_bf16 v[68:71], v[148:151], v[200:203], v[68:71]
	v_mfma_f32_16x16x32_bf16 v[64:67], v[168:171], v[200:203], v[64:67]
	s_barrier
	s_add_u32 s6, s6, 0x18080
	s_addc_u32 s7, s7, 0
	s_add_i32 s8, s8, s44
	s_mov_b32 m0, s8
	s_nop 0
	global_load_lds_dwordx4 v130, s[6:7]
	s_add_i32 m0, s8, 0x2000
	s_nop 0
	global_load_lds_dwordx4 v134, s[6:7]
	s_waitcnt vmcnt(6)
	s_barrier
	v_mfma_f32_16x16x32_bf16 v[28:31], v[204:207], v[172:175], v[28:31]
	v_mfma_f32_16x16x32_bf16 v[24:27], v[212:215], v[172:175], v[24:27]
	v_mfma_f32_16x16x32_bf16 v[20:23], v[204:207], v[180:183], v[20:23]
	v_mfma_f32_16x16x32_bf16 v[16:19], v[212:215], v[180:183], v[16:19]
	v_mfma_f32_16x16x32_bf16 v[12:15], v[204:207], v[188:191], v[12:15]
	v_mfma_f32_16x16x32_bf16 v[8:11], v[212:215], v[188:191], v[8:11]
	v_mfma_f32_16x16x32_bf16 v[4:7], v[204:207], v[196:199], v[4:7]
	v_mfma_f32_16x16x32_bf16 v[0:3], v[212:215], v[196:199], v[0:3]
	v_mfma_f32_16x16x32_bf16 v[28:31], v[208:211], v[176:179], v[28:31]
	v_mfma_f32_16x16x32_bf16 v[24:27], v[216:219], v[176:179], v[24:27]
	v_mfma_f32_16x16x32_bf16 v[20:23], v[208:211], v[184:187], v[20:23]
	v_mfma_f32_16x16x32_bf16 v[16:19], v[216:219], v[184:187], v[16:19]
	v_mfma_f32_16x16x32_bf16 v[12:15], v[208:211], v[192:195], v[12:15]
	v_mfma_f32_16x16x32_bf16 v[8:11], v[216:219], v[192:195], v[8:11]
	v_mfma_f32_16x16x32_bf16 v[4:7], v[208:211], v[200:203], v[4:7]
	v_mfma_f32_16x16x32_bf16 v[0:3], v[216:219], v[200:203], v[0:3]
	s_add_i32 s60, s60, 2
	s_add_u32 s35, s35, 0x100
	s_addc_u32 s37, s37, 0
	s_cmp_gt_u32 s60, 3
	s_mov_b64 s[8:9], s[4:5]
	s_barrier
	s_cbranch_scc0 .LBB0_321
	s_lshl_b32 s37, s34, 8
	s_ashr_i32 s6, s34, 1
	s_cmp_lt_i32 s6, 2
	s_cselect_b64 s[8:9], -1, 0
	s_cmp_gt_i32 s6, 1
	s_cselect_b64 s[34:35], -1, 0
	s_lshl_b32 s60, s6, 9
	s_add_i32 s61, s60, 0xfffffc00
	v_bitop3_b32 v144, s37, v161, v156 bitop3:0xc8
	v_or_b32_e32 v146, s61, v144
	v_or_b32_e32 v144, s60, v144
	v_mov_b32_e32 v145, 0
	s_cmp_lt_i32 s6, 4
	v_cndmask_b32_e64 v152, v146, v144, s[8:9]
	s_cselect_b64 s[4:5], -1, 0
	s_cmp_gt_i32 s6, 3
	v_ashrrev_i32_e32 v153, 31, v152
	v_mov_b32_e32 v144, v145
	s_cbranch_scc1 .LBB0_330
	s_and_b64 s[10:11], s[8:9], exec
	s_cselect_b32 s7, s21, s23
	s_cselect_b32 s10, s20, s22
	v_mov_b32_e32 v146, s10
	v_mov_b32_e32 v147, s7
	v_lshl_add_u64 v[146:147], v[152:153], 2, v[146:147]
	global_load_dword v144, v[146:147], off
	v_cndmask_b32_e64 v146, 0, 1, s[4:5]
	v_cmp_ne_u32_e64 s[10:11], 1, v146
	s_andn2_b64 vcc, exec, s[4:5]
	s_cbranch_vccz .LBB0_331

.LBB0_998:
	s_add_u32 s20, s10, 0x100
	s_addc_u32 s21, s11, 0
	s_add_i32 s60, 0, 0x10000
	v_add_u32_e32 v142, s60, v145
	ds_read_b128 v[138:141], v142
	ds_read_b128 v[148:151], v142 offset:1024
	ds_read_b128 v[152:155], v142 offset:2048
	ds_read_b128 v[156:159], v142 offset:3072
	s_cmp_eq_u32 s59, 40
	s_cselect_b32 s25, s7, s21
	s_cselect_b32 s24, s6, s20
	s_cselect_b32 s23, s9, s58
	s_cselect_b32 s22, s8, s57
	s_add_i32 m0, s34, 0xc000
	ds_read_b128 v[160:163], v147
	ds_read_b128 v[164:167], v147 offset:1024
	ds_read_b128 v[168:171], v147 offset:2048
	ds_read_b128 v[172:175], v147 offset:3072
	ds_read_b128 v[176:179], v147 offset:4096
	ds_read_b128 v[180:183], v147 offset:5120
	ds_read_b128 v[184:187], v147 offset:6144
	ds_read_b128 v[188:191], v147 offset:7168
	global_load_lds_dwordx4 v134, s[10:11]
	s_add_i32 m0, s34, 0xe000
	s_nop 0
	global_load_lds_dwordx4 v136, s[10:11]
	s_waitcnt lgkmcnt(8)
	s_barrier
	s_waitcnt lgkmcnt(0)
	v_mfma_f32_16x16x32_bf16 v[124:127], v[138:141], v[160:163], v[124:127]
	v_mfma_f32_16x16x32_bf16 v[120:123], v[152:155], v[160:163], v[120:123]
	v_mfma_f32_16x16x32_bf16 v[108:111], v[138:141], v[168:171], v[108:111]
	v_mfma_f32_16x16x32_bf16 v[104:107], v[152:155], v[168:171], v[104:107]
	v_mfma_f32_16x16x32_bf16 v[92:95], v[138:141], v[176:179], v[92:95]
	v_mfma_f32_16x16x32_bf16 v[88:91], v[152:155], v[176:179], v[88:91]
	v_mfma_f32_16x16x32_bf16 v[76:79], v[138:141], v[184:187], v[76:79]
	v_mfma_f32_16x16x32_bf16 v[72:75], v[152:155], v[184:187], v[72:75]
	v_mfma_f32_16x16x32_bf16 v[124:127], v[148:151], v[164:167], v[124:127]
	v_mfma_f32_16x16x32_bf16 v[120:123], v[156:159], v[164:167], v[120:123]
	v_mfma_f32_16x16x32_bf16 v[108:111], v[148:151], v[172:175], v[108:111]
	v_mfma_f32_16x16x32_bf16 v[104:107], v[156:159], v[172:175], v[104:107]
	v_mfma_f32_16x16x32_bf16 v[92:95], v[148:151], v[180:183], v[92:95]
	v_mfma_f32_16x16x32_bf16 v[88:91], v[156:159], v[180:183], v[88:91]
	v_mfma_f32_16x16x32_bf16 v[76:79], v[148:151], v[188:191], v[76:79]
	v_mfma_f32_16x16x32_bf16 v[72:75], v[156:159], v[188:191], v[72:75]
	s_barrier
	s_add_i32 s61, 0, 0x14000
	v_add_u32_e32 v142, s61, v145
	s_add_i32 s10, s60, s27
	ds_read_b128 v[192:195], v142
	ds_read_b128 v[196:199], v142 offset:1024
	ds_read_b128 v[200:203], v142 offset:2048
	ds_read_b128 v[204:207], v142 offset:3072
	s_add_u32 s98, s22, s40
	s_addc_u32 s99, s23, s41
	s_mov_b32 m0, s10
	s_nop 0
	global_load_lds_dwordx4 v208, s[22:23]
	s_add_i32 m0, s10, 0x2000
	s_nop 0
	global_load_lds_dwordx4 v128, s[22:23]
	s_barrier
	s_waitcnt lgkmcnt(0)
	v_mfma_f32_16x16x32_bf16 v[116:119], v[192:195], v[160:163], v[116:119]
	v_mfma_f32_16x16x32_bf16 v[112:115], v[200:203], v[160:163], v[112:115]
	v_mfma_f32_16x16x32_bf16 v[100:103], v[192:195], v[168:171], v[100:103]
	v_mfma_f32_16x16x32_bf16 v[96:99], v[200:203], v[168:171], v[96:99]
	v_mfma_f32_16x16x32_bf16 v[84:87], v[192:195], v[176:179], v[84:87]
	v_mfma_f32_16x16x32_bf16 v[80:83], v[200:203], v[176:179], v[80:83]
	v_mfma_f32_16x16x32_bf16 v[68:71], v[192:195], v[184:187], v[68:71]
	v_mfma_f32_16x16x32_bf16 v[64:67], v[200:203], v[184:187], v[64:67]
	v_mfma_f32_16x16x32_bf16 v[116:119], v[196:199], v[164:167], v[116:119]
	v_mfma_f32_16x16x32_bf16 v[112:115], v[204:207], v[164:167], v[112:115]
	v_mfma_f32_16x16x32_bf16 v[100:103], v[196:199], v[172:175], v[100:103]
	v_mfma_f32_16x16x32_bf16 v[96:99], v[204:207], v[172:175], v[96:99]
	v_mfma_f32_16x16x32_bf16 v[84:87], v[196:199], v[180:183], v[84:87]
	v_mfma_f32_16x16x32_bf16 v[80:83], v[204:207], v[180:183], v[80:83]
	v_mfma_f32_16x16x32_bf16 v[68:71], v[196:199], v[188:191], v[68:71]
	v_mfma_f32_16x16x32_bf16 v[64:67], v[204:207], v[188:191], v[64:67]
	s_mov_b32 m0, s34
	s_add_u32 s100, s24, s40
	s_addc_u32 s101, s25, s41
	s_barrier
	ds_read_b128 v[160:163], v147 offset:16384
	ds_read_b128 v[164:167], v147 offset:17408
	ds_read_b128 v[168:171], v147 offset:18432
	ds_read_b128 v[172:175], v147 offset:19456
	ds_read_b128 v[176:179], v147 offset:20480
	ds_read_b128 v[180:183], v147 offset:21504
	ds_read_b128 v[184:187], v147 offset:22528
	ds_read_b128 v[188:191], v147 offset:23552
	global_load_lds_dwordx4 v132, s[24:25]
	s_mov_b32 m0, s35
	s_nop 0
	global_load_lds_dwordx4 v130, s[24:25]
	s_barrier
	s_waitcnt lgkmcnt(0)
	v_mfma_f32_16x16x32_bf16 v[60:63], v[138:141], v[160:163], v[60:63]
	v_mfma_f32_16x16x32_bf16 v[56:59], v[152:155], v[160:163], v[56:59]
	v_mfma_f32_16x16x32_bf16 v[44:47], v[138:141], v[168:171], v[44:47]
	v_mfma_f32_16x16x32_bf16 v[40:43], v[152:155], v[168:171], v[40:43]
	v_mfma_f32_16x16x32_bf16 v[28:31], v[138:141], v[176:179], v[28:31]
	v_mfma_f32_16x16x32_bf16 v[24:27], v[152:155], v[176:179], v[24:27]
	v_mfma_f32_16x16x32_bf16 v[12:15], v[138:141], v[184:187], v[12:15]
	v_mfma_f32_16x16x32_bf16 v[8:11], v[152:155], v[184:187], v[8:11]
	v_mfma_f32_16x16x32_bf16 v[60:63], v[148:151], v[164:167], v[60:63]
	v_mfma_f32_16x16x32_bf16 v[56:59], v[156:159], v[164:167], v[56:59]
	v_mfma_f32_16x16x32_bf16 v[44:47], v[148:151], v[172:175], v[44:47]
	v_mfma_f32_16x16x32_bf16 v[40:43], v[156:159], v[172:175], v[40:43]
	v_mfma_f32_16x16x32_bf16 v[28:31], v[148:151], v[180:183], v[28:31]
	v_mfma_f32_16x16x32_bf16 v[24:27], v[156:159], v[180:183], v[24:27]
	v_mfma_f32_16x16x32_bf16 v[12:15], v[148:151], v[188:191], v[12:15]
	v_mfma_f32_16x16x32_bf16 v[8:11], v[156:159], v[188:191], v[8:11]
	s_barrier
	s_add_u32 s10, s22, 0xb0000
	s_addc_u32 s11, s23, 0
	s_add_i32 s60, s61, s27
	s_mov_b32 m0, s60
	s_nop 0
	global_load_lds_dwordx4 v208, s[10:11]
	s_add_i32 m0, s60, 0x2000
	s_nop 0
	global_load_lds_dwordx4 v128, s[10:11]
	s_waitcnt vmcnt(6)
	s_barrier
	v_mfma_f32_16x16x32_bf16 v[52:55], v[192:195], v[160:163], v[52:55]
	v_mfma_f32_16x16x32_bf16 v[48:51], v[200:203], v[160:163], v[48:51]
	v_mfma_f32_16x16x32_bf16 v[36:39], v[192:195], v[168:171], v[36:39]
	v_mfma_f32_16x16x32_bf16 v[32:35], v[200:203], v[168:171], v[32:35]
	v_mfma_f32_16x16x32_bf16 v[20:23], v[192:195], v[176:179], v[20:23]
	v_mfma_f32_16x16x32_bf16 v[16:19], v[200:203], v[176:179], v[16:19]
	v_mfma_f32_16x16x32_bf16 v[4:7], v[192:195], v[184:187], v[4:7]
	v_mfma_f32_16x16x32_bf16 v[0:3], v[200:203], v[184:187], v[0:3]
	v_mfma_f32_16x16x32_bf16 v[52:55], v[196:199], v[164:167], v[52:55]
	v_mfma_f32_16x16x32_bf16 v[48:51], v[204:207], v[164:167], v[48:51]
	v_mfma_f32_16x16x32_bf16 v[36:39], v[196:199], v[172:175], v[36:39]
	v_mfma_f32_16x16x32_bf16 v[32:35], v[204:207], v[172:175], v[32:35]
	v_mfma_f32_16x16x32_bf16 v[20:23], v[196:199], v[180:183], v[20:23]
	v_mfma_f32_16x16x32_bf16 v[16:19], v[204:207], v[180:183], v[16:19]
	v_mfma_f32_16x16x32_bf16 v[4:7], v[196:199], v[188:191], v[4:7]
	v_mfma_f32_16x16x32_bf16 v[0:3], v[204:207], v[188:191], v[0:3]
	s_add_i32 s60, 0, 0x18000
	v_add_u32_e32 v156, s60, v145
	s_barrier
	ds_read_b128 v[138:141], v156
	ds_read_b128 v[148:151], v156 offset:1024
	ds_read_b128 v[152:155], v156 offset:2048
	ds_read_b128 v[156:159], v156 offset:3072
	s_add_u32 s10, s24, 0xb0000
	s_addc_u32 s11, s25, 0
	s_mov_b32 m0, s36
	ds_read_b128 v[160:163], v147 offset:32768
	ds_read_b128 v[164:167], v147 offset:33792
	ds_read_b128 v[168:171], v147 offset:34816
	ds_read_b128 v[172:175], v147 offset:35840
	ds_read_b128 v[176:179], v147 offset:36864
	ds_read_b128 v[180:183], v147 offset:37888
	ds_read_b128 v[184:187], v147 offset:38912
	ds_read_b128 v[188:191], v147 offset:39936
	global_load_lds_dwordx4 v132, s[10:11]
	s_mov_b32 m0, s46
	s_nop 0
	global_load_lds_dwordx4 v130, s[10:11]
	s_waitcnt lgkmcnt(8)
	s_barrier
	s_waitcnt lgkmcnt(0)
	v_mfma_f32_16x16x32_bf16 v[124:127], v[138:141], v[160:163], v[124:127]
	v_mfma_f32_16x16x32_bf16 v[120:123], v[152:155], v[160:163], v[120:123]
	v_mfma_f32_16x16x32_bf16 v[108:111], v[138:141], v[168:171], v[108:111]
	v_mfma_f32_16x16x32_bf16 v[104:107], v[152:155], v[168:171], v[104:107]
	v_mfma_f32_16x16x32_bf16 v[92:95], v[138:141], v[176:179], v[92:95]
	v_mfma_f32_16x16x32_bf16 v[88:91], v[152:155], v[176:179], v[88:91]
	v_mfma_f32_16x16x32_bf16 v[76:79], v[138:141], v[184:187], v[76:79]
	v_mfma_f32_16x16x32_bf16 v[72:75], v[152:155], v[184:187], v[72:75]
	v_mfma_f32_16x16x32_bf16 v[124:127], v[148:151], v[164:167], v[124:127]
	v_mfma_f32_16x16x32_bf16 v[120:123], v[156:159], v[164:167], v[120:123]
	v_mfma_f32_16x16x32_bf16 v[108:111], v[148:151], v[172:175], v[108:111]
	v_mfma_f32_16x16x32_bf16 v[104:107], v[156:159], v[172:175], v[104:107]
	v_mfma_f32_16x16x32_bf16 v[92:95], v[148:151], v[180:183], v[92:95]
	v_mfma_f32_16x16x32_bf16 v[88:91], v[156:159], v[180:183], v[88:91]
	v_mfma_f32_16x16x32_bf16 v[76:79], v[148:151], v[188:191], v[76:79]
	v_mfma_f32_16x16x32_bf16 v[72:75], v[156:159], v[188:191], v[72:75]
	s_barrier
	s_add_i32 s24, 0, 0x1c000
	s_add_i32 s10, s60, s27
	v_add_u32_e32 v204, s24, v145
	s_mov_b32 m0, s10
	ds_read_b128 v[192:195], v204
	ds_read_b128 v[196:199], v204 offset:1024
	ds_read_b128 v[200:203], v204 offset:2048
	ds_read_b128 v[204:207], v204 offset:3072
	global_load_lds_dwordx4 v208, s[98:99]
	s_add_i32 m0, s10, 0x2000
	s_nop 0
	global_load_lds_dwordx4 v128, s[98:99]
	s_barrier
	s_waitcnt lgkmcnt(0)
	v_mfma_f32_16x16x32_bf16 v[116:119], v[192:195], v[160:163], v[116:119]
	v_mfma_f32_16x16x32_bf16 v[112:115], v[200:203], v[160:163], v[112:115]
	v_mfma_f32_16x16x32_bf16 v[100:103], v[192:195], v[168:171], v[100:103]
	v_mfma_f32_16x16x32_bf16 v[96:99], v[200:203], v[168:171], v[96:99]
	v_mfma_f32_16x16x32_bf16 v[84:87], v[192:195], v[176:179], v[84:87]
	v_mfma_f32_16x16x32_bf16 v[80:83], v[200:203], v[176:179], v[80:83]
	v_mfma_f32_16x16x32_bf16 v[68:71], v[192:195], v[184:187], v[68:71]
	v_mfma_f32_16x16x32_bf16 v[64:67], v[200:203], v[184:187], v[64:67]
	v_mfma_f32_16x16x32_bf16 v[116:119], v[196:199], v[164:167], v[116:119]
	v_mfma_f32_16x16x32_bf16 v[112:115], v[204:207], v[164:167], v[112:115]
	v_mfma_f32_16x16x32_bf16 v[100:103], v[196:199], v[172:175], v[100:103]
	v_mfma_f32_16x16x32_bf16 v[96:99], v[204:207], v[172:175], v[96:99]
	v_mfma_f32_16x16x32_bf16 v[84:87], v[196:199], v[180:183], v[84:87]
	v_mfma_f32_16x16x32_bf16 v[80:83], v[204:207], v[180:183], v[80:83]
	v_mfma_f32_16x16x32_bf16 v[68:71], v[196:199], v[188:191], v[68:71]
	v_mfma_f32_16x16x32_bf16 v[64:67], v[204:207], v[188:191], v[64:67]
	s_mov_b32 m0, s50
	s_barrier
	ds_read_b128 v[160:163], v147 offset:49152
	ds_read_b128 v[164:167], v147 offset:50176
	ds_read_b128 v[168:171], v147 offset:51200
	ds_read_b128 v[172:175], v147 offset:52224
	ds_read_b128 v[176:179], v147 offset:53248
	ds_read_b128 v[180:183], v147 offset:54272
	ds_read_b128 v[184:187], v147 offset:55296
	ds_read_b128 v[188:191], v147 offset:56320
	global_load_lds_dwordx4 v132, s[100:101]
	s_mov_b32 m0, s51
	s_nop 0
	global_load_lds_dwordx4 v130, s[100:101]
	s_barrier
	s_waitcnt lgkmcnt(0)
	v_mfma_f32_16x16x32_bf16 v[60:63], v[138:141], v[160:163], v[60:63]
	v_mfma_f32_16x16x32_bf16 v[56:59], v[152:155], v[160:163], v[56:59]
	v_mfma_f32_16x16x32_bf16 v[44:47], v[138:141], v[168:171], v[44:47]
	v_mfma_f32_16x16x32_bf16 v[40:43], v[152:155], v[168:171], v[40:43]
	v_mfma_f32_16x16x32_bf16 v[28:31], v[138:141], v[176:179], v[28:31]
	v_mfma_f32_16x16x32_bf16 v[24:27], v[152:155], v[176:179], v[24:27]
	v_mfma_f32_16x16x32_bf16 v[12:15], v[138:141], v[184:187], v[12:15]
	v_mfma_f32_16x16x32_bf16 v[8:11], v[152:155], v[184:187], v[8:11]
	v_mfma_f32_16x16x32_bf16 v[60:63], v[148:151], v[164:167], v[60:63]
	v_mfma_f32_16x16x32_bf16 v[56:59], v[156:159], v[164:167], v[56:59]
	v_mfma_f32_16x16x32_bf16 v[44:47], v[148:151], v[172:175], v[44:47]
	v_mfma_f32_16x16x32_bf16 v[40:43], v[156:159], v[172:175], v[40:43]
	v_mfma_f32_16x16x32_bf16 v[28:31], v[148:151], v[180:183], v[28:31]
	v_mfma_f32_16x16x32_bf16 v[24:27], v[156:159], v[180:183], v[24:27]
	v_mfma_f32_16x16x32_bf16 v[12:15], v[148:151], v[188:191], v[12:15]
	v_mfma_f32_16x16x32_bf16 v[8:11], v[156:159], v[188:191], v[8:11]
	s_barrier
	s_add_u32 s10, s22, 0xb0080
	s_addc_u32 s11, s23, 0
	s_add_i32 s22, s24, s27
	s_mov_b32 m0, s22
	s_nop 0
	global_load_lds_dwordx4 v208, s[10:11]
	s_add_i32 m0, s22, 0x2000
	s_nop 0
	global_load_lds_dwordx4 v128, s[10:11]
	s_waitcnt vmcnt(6)
	s_barrier
	v_mfma_f32_16x16x32_bf16 v[52:55], v[192:195], v[160:163], v[52:55]
	v_mfma_f32_16x16x32_bf16 v[48:51], v[200:203], v[160:163], v[48:51]
	v_mfma_f32_16x16x32_bf16 v[36:39], v[192:195], v[168:171], v[36:39]
	v_mfma_f32_16x16x32_bf16 v[32:35], v[200:203], v[168:171], v[32:35]
	v_mfma_f32_16x16x32_bf16 v[20:23], v[192:195], v[176:179], v[20:23]
	v_mfma_f32_16x16x32_bf16 v[16:19], v[200:203], v[176:179], v[16:19]
	v_mfma_f32_16x16x32_bf16 v[4:7], v[192:195], v[184:187], v[4:7]
	v_mfma_f32_16x16x32_bf16 v[0:3], v[200:203], v[184:187], v[0:3]
	v_mfma_f32_16x16x32_bf16 v[52:55], v[196:199], v[164:167], v[52:55]
	v_mfma_f32_16x16x32_bf16 v[48:51], v[204:207], v[164:167], v[48:51]
	v_mfma_f32_16x16x32_bf16 v[36:39], v[196:199], v[172:175], v[36:39]
	v_mfma_f32_16x16x32_bf16 v[32:35], v[204:207], v[172:175], v[32:35]
	v_mfma_f32_16x16x32_bf16 v[20:23], v[196:199], v[180:183], v[20:23]
	v_mfma_f32_16x16x32_bf16 v[16:19], v[204:207], v[180:183], v[16:19]
	v_mfma_f32_16x16x32_bf16 v[4:7], v[196:199], v[188:191], v[4:7]
	v_mfma_f32_16x16x32_bf16 v[0:3], v[204:207], v[188:191], v[0:3]
	s_add_i32 s59, s59, 2
	s_add_u32 s57, s57, 0x100
	s_addc_u32 s58, s58, 0
	s_cmp_gt_u32 s59, 41
	s_mov_b64 s[10:11], s[20:21]
	s_barrier
	s_cbranch_scc0 .LBB0_998
	v_lshl_add_u32 v142, s39, 8, v144
	v_lshl_or_b32 v143, s38, 8, v146
	s_and_b64 vcc, exec, s[4:5]
	s_mov_b32 s38, s53
	s_mov_b32 s39, s56
	s_mov_b64 s[20:21], s[8:9]
	s_mov_b64 s[10:11], s[6:7]
	v_lshl_add_u32 v210, v142, 10, v143
	v_lshlrev_b32_e32 v211, 2, v210
	v_lshlrev_b32_e32 v210, 1, v210
	global_load_dwordx4 v[148:151], v210, s[14:15]
	global_load_dwordx4 v[152:155], v210, s[14:15] offset:256
	v_add_u32_e32 v210, 0x8000, v210
	global_load_dwordx4 v[156:159], v210, s[14:15]
	global_load_dwordx4 v[160:163], v210, s[14:15] offset:256
	v_add_u32_e32 v210, 0x8000, v210
	global_load_dwordx4 v[164:167], v210, s[14:15]
	global_load_dwordx4 v[168:171], v210, s[14:15] offset:256
	v_add_u32_e32 v210, 0x8000, v210
	global_load_dwordx4 v[172:175], v210, s[14:15]
	global_load_dwordx4 v[176:179], v210, s[14:15] offset:256
	v_add_u32_e32 v210, 0x28000, v210
	global_load_dwordx4 v[180:183], v210, s[14:15]
	global_load_dwordx4 v[184:187], v210, s[14:15] offset:256
	v_add_u32_e32 v210, 0x8000, v210
	global_load_dwordx4 v[188:191], v210, s[14:15]
	global_load_dwordx4 v[192:195], v210, s[14:15] offset:256
	v_add_u32_e32 v210, 0x8000, v210
	global_load_dwordx4 v[196:199], v210, s[14:15]
	global_load_dwordx4 v[200:203], v210, s[14:15] offset:256
	v_add_u32_e32 v210, 0x8000, v210
	s_waitcnt vmcnt(12)
	v_lshlrev_b32_e32 v204, 16, v148
	v_and_b32_e32 v205, 0xffff0000, v148
	v_lshlrev_b32_e32 v206, 16, v149
	v_and_b32_e32 v207, 0xffff0000, v149
	v_pk_add_f32 v[124:125], v[124:125], v[204:205]
	v_pk_add_f32 v[126:127], v[126:127], v[206:207]
	v_lshlrev_b32_e32 v204, 16, v150
	v_and_b32_e32 v205, 0xffff0000, v150
	v_lshlrev_b32_e32 v206, 16, v151
	v_and_b32_e32 v207, 0xffff0000, v151
	v_pk_add_f32 v[120:121], v[120:121], v[204:205]
	v_pk_add_f32 v[122:123], v[122:123], v[206:207]
	global_store_dwordx4 v211, v[124:127], s[16:17]
	global_store_dwordx4 v211, v[120:123], s[16:17] offset:16
	v_lshlrev_b32_e32 v204, 16, v152
	v_and_b32_e32 v205, 0xffff0000, v152
	v_lshlrev_b32_e32 v206, 16, v153
	v_and_b32_e32 v207, 0xffff0000, v153
	v_pk_add_f32 v[116:117], v[116:117], v[204:205]
	v_pk_add_f32 v[118:119], v[118:119], v[206:207]
	v_lshlrev_b32_e32 v204, 16, v154
	v_and_b32_e32 v205, 0xffff0000, v154
	v_lshlrev_b32_e32 v206, 16, v155
	v_and_b32_e32 v207, 0xffff0000, v155
	v_pk_add_f32 v[112:113], v[112:113], v[204:205]
	v_pk_add_f32 v[114:115], v[114:115], v[206:207]
	global_store_dwordx4 v211, v[116:119], s[16:17] offset:512
	global_store_dwordx4 v211, v[112:115], s[16:17] offset:528
	v_add_u32_e32 v211, 0x10000, v211
	global_load_dwordx4 v[148:151], v210, s[14:15]
	global_load_dwordx4 v[152:155], v210, s[14:15] offset:256
	s_waitcnt vmcnt(16)
	v_lshlrev_b32_e32 v204, 16, v156
	v_and_b32_e32 v205, 0xffff0000, v156
	v_lshlrev_b32_e32 v206, 16, v157
	v_and_b32_e32 v207, 0xffff0000, v157
	v_pk_add_f32 v[108:109], v[108:109], v[204:205]
	v_pk_add_f32 v[110:111], v[110:111], v[206:207]
	v_lshlrev_b32_e32 v204, 16, v158
	v_and_b32_e32 v205, 0xffff0000, v158
	v_lshlrev_b32_e32 v206, 16, v159
	v_and_b32_e32 v207, 0xffff0000, v159
	v_pk_add_f32 v[104:105], v[104:105], v[204:205]
	v_pk_add_f32 v[106:107], v[106:107], v[206:207]
	global_store_dwordx4 v211, v[108:111], s[16:17]
	global_store_dwordx4 v211, v[104:107], s[16:17] offset:16
	v_lshlrev_b32_e32 v204, 16, v160
	v_and_b32_e32 v205, 0xffff0000, v160
	v_lshlrev_b32_e32 v206, 16, v161
	v_and_b32_e32 v207, 0xffff0000, v161
	v_pk_add_f32 v[100:101], v[100:101], v[204:205]
	v_pk_add_f32 v[102:103], v[102:103], v[206:207]
	v_lshlrev_b32_e32 v204, 16, v162
	v_and_b32_e32 v205, 0xffff0000, v162
	v_lshlrev_b32_e32 v206, 16, v163
	v_and_b32_e32 v207, 0xffff0000, v163
	v_pk_add_f32 v[96:97], v[96:97], v[204:205]
	v_pk_add_f32 v[98:99], v[98:99], v[206:207]
	global_store_dwordx4 v211, v[100:103], s[16:17] offset:512
	global_store_dwordx4 v211, v[96:99], s[16:17] offset:528
	v_add_u32_e32 v211, 0x10000, v211
	s_waitcnt vmcnt(18)
	v_lshlrev_b32_e32 v204, 16, v164
	v_and_b32_e32 v205, 0xffff0000, v164
	v_lshlrev_b32_e32 v206, 16, v165
	v_and_b32_e32 v207, 0xffff0000, v165
	v_pk_add_f32 v[92:93], v[92:93], v[204:205]
	v_pk_add_f32 v[94:95], v[94:95], v[206:207]
	v_lshlrev_b32_e32 v204, 16, v166
	v_and_b32_e32 v205, 0xffff0000, v166
	v_lshlrev_b32_e32 v206, 16, v167
	v_and_b32_e32 v207, 0xffff0000, v167
	v_pk_add_f32 v[88:89], v[88:89], v[204:205]
	v_pk_add_f32 v[90:91], v[90:91], v[206:207]
	global_store_dwordx4 v211, v[92:95], s[16:17]
	global_store_dwordx4 v211, v[88:91], s[16:17] offset:16
	v_lshlrev_b32_e32 v204, 16, v168
	v_and_b32_e32 v205, 0xffff0000, v168
	v_lshlrev_b32_e32 v206, 16, v169
	v_and_b32_e32 v207, 0xffff0000, v169
	v_pk_add_f32 v[84:85], v[84:85], v[204:205]
	v_pk_add_f32 v[86:87], v[86:87], v[206:207]
	v_lshlrev_b32_e32 v204, 16, v170
	v_and_b32_e32 v205, 0xffff0000, v170
	v_lshlrev_b32_e32 v206, 16, v171
	v_and_b32_e32 v207, 0xffff0000, v171
	v_pk_add_f32 v[80:81], v[80:81], v[204:205]
	v_pk_add_f32 v[82:83], v[82:83], v[206:207]
	global_store_dwordx4 v211, v[84:87], s[16:17] offset:512
	global_store_dwordx4 v211, v[80:83], s[16:17] offset:528
	v_add_u32_e32 v211, 0x10000, v211
	s_waitcnt vmcnt(20)
	v_lshlrev_b32_e32 v204, 16, v172
	v_and_b32_e32 v205, 0xffff0000, v172
	v_lshlrev_b32_e32 v206, 16, v173
	v_and_b32_e32 v207, 0xffff0000, v173
	v_pk_add_f32 v[76:77], v[76:77], v[204:205]
	v_pk_add_f32 v[78:79], v[78:79], v[206:207]
	v_lshlrev_b32_e32 v204, 16, v174
	v_and_b32_e32 v205, 0xffff0000, v174
	v_lshlrev_b32_e32 v206, 16, v175
	v_and_b32_e32 v207, 0xffff0000, v175
	v_pk_add_f32 v[72:73], v[72:73], v[204:205]
	v_pk_add_f32 v[74:75], v[74:75], v[206:207]
	global_store_dwordx4 v211, v[76:79], s[16:17]
	global_store_dwordx4 v211, v[72:75], s[16:17] offset:16
	v_lshlrev_b32_e32 v204, 16, v176
	v_and_b32_e32 v205, 0xffff0000, v176
	v_lshlrev_b32_e32 v206, 16, v177
	v_and_b32_e32 v207, 0xffff0000, v177
	v_pk_add_f32 v[68:69], v[68:69], v[204:205]
	v_pk_add_f32 v[70:71], v[70:71], v[206:207]
	v_lshlrev_b32_e32 v204, 16, v178
	v_and_b32_e32 v205, 0xffff0000, v178
	v_lshlrev_b32_e32 v206, 16, v179
	v_and_b32_e32 v207, 0xffff0000, v179
	v_pk_add_f32 v[64:65], v[64:65], v[204:205]
	v_pk_add_f32 v[66:67], v[66:67], v[206:207]
	global_store_dwordx4 v211, v[68:71], s[16:17] offset:512
	global_store_dwordx4 v211, v[64:67], s[16:17] offset:528
	v_add_u32_e32 v211, 0x50000, v211
	s_waitcnt vmcnt(22)
	v_lshlrev_b32_e32 v204, 16, v180
	v_and_b32_e32 v205, 0xffff0000, v180
	v_lshlrev_b32_e32 v206, 16, v181
	v_and_b32_e32 v207, 0xffff0000, v181
	v_pk_add_f32 v[60:61], v[60:61], v[204:205]
	v_pk_add_f32 v[62:63], v[62:63], v[206:207]
	v_lshlrev_b32_e32 v204, 16, v182
	v_and_b32_e32 v205, 0xffff0000, v182
	v_lshlrev_b32_e32 v206, 16, v183
	v_and_b32_e32 v207, 0xffff0000, v183
	v_pk_add_f32 v[56:57], v[56:57], v[204:205]
	v_pk_add_f32 v[58:59], v[58:59], v[206:207]
	global_store_dwordx4 v211, v[60:63], s[16:17]
	global_store_dwordx4 v211, v[56:59], s[16:17] offset:16
	v_lshlrev_b32_e32 v204, 16, v184
	v_and_b32_e32 v205, 0xffff0000, v184
	v_lshlrev_b32_e32 v206, 16, v185
	v_and_b32_e32 v207, 0xffff0000, v185
	v_pk_add_f32 v[52:53], v[52:53], v[204:205]
	v_pk_add_f32 v[54:55], v[54:55], v[206:207]
	v_lshlrev_b32_e32 v204, 16, v186
	v_and_b32_e32 v205, 0xffff0000, v186
	v_lshlrev_b32_e32 v206, 16, v187
	v_and_b32_e32 v207, 0xffff0000, v187
	v_pk_add_f32 v[48:49], v[48:49], v[204:205]
	v_pk_add_f32 v[50:51], v[50:51], v[206:207]
	global_store_dwordx4 v211, v[52:55], s[16:17] offset:512
	global_store_dwordx4 v211, v[48:51], s[16:17] offset:528
	v_add_u32_e32 v211, 0x10000, v211
	s_waitcnt vmcnt(24)
	v_lshlrev_b32_e32 v204, 16, v188
	v_and_b32_e32 v205, 0xffff0000, v188
	v_lshlrev_b32_e32 v206, 16, v189
	v_and_b32_e32 v207, 0xffff0000, v189
	v_pk_add_f32 v[44:45], v[44:45], v[204:205]
	v_pk_add_f32 v[46:47], v[46:47], v[206:207]
	v_lshlrev_b32_e32 v204, 16, v190
	v_and_b32_e32 v205, 0xffff0000, v190
	v_lshlrev_b32_e32 v206, 16, v191
	v_and_b32_e32 v207, 0xffff0000, v191
	v_pk_add_f32 v[40:41], v[40:41], v[204:205]
	v_pk_add_f32 v[42:43], v[42:43], v[206:207]
	global_store_dwordx4 v211, v[44:47], s[16:17]
	global_store_dwordx4 v211, v[40:43], s[16:17] offset:16
	v_lshlrev_b32_e32 v204, 16, v192
	v_and_b32_e32 v205, 0xffff0000, v192
	v_lshlrev_b32_e32 v206, 16, v193
	v_and_b32_e32 v207, 0xffff0000, v193
	v_pk_add_f32 v[36:37], v[36:37], v[204:205]
	v_pk_add_f32 v[38:39], v[38:39], v[206:207]
	v_lshlrev_b32_e32 v204, 16, v194
	v_and_b32_e32 v205, 0xffff0000, v194
	v_lshlrev_b32_e32 v206, 16, v195
	v_and_b32_e32 v207, 0xffff0000, v195
	v_pk_add_f32 v[32:33], v[32:33], v[204:205]
	v_pk_add_f32 v[34:35], v[34:35], v[206:207]
	global_store_dwordx4 v211, v[36:39], s[16:17] offset:512
	global_store_dwordx4 v211, v[32:35], s[16:17] offset:528
	v_add_u32_e32 v211, 0x10000, v211
	s_waitcnt vmcnt(26)
	v_lshlrev_b32_e32 v204, 16, v196
	v_and_b32_e32 v205, 0xffff0000, v196
	v_lshlrev_b32_e32 v206, 16, v197
	v_and_b32_e32 v207, 0xffff0000, v197
	v_pk_add_f32 v[28:29], v[28:29], v[204:205]
	v_pk_add_f32 v[30:31], v[30:31], v[206:207]
	v_lshlrev_b32_e32 v204, 16, v198
	v_and_b32_e32 v205, 0xffff0000, v198
	v_lshlrev_b32_e32 v206, 16, v199
	v_and_b32_e32 v207, 0xffff0000, v199
	v_pk_add_f32 v[24:25], v[24:25], v[204:205]
	v_pk_add_f32 v[26:27], v[26:27], v[206:207]
	global_store_dwordx4 v211, v[28:31], s[16:17]
	global_store_dwordx4 v211, v[24:27], s[16:17] offset:16
	v_lshlrev_b32_e32 v204, 16, v200
	v_and_b32_e32 v205, 0xffff0000, v200
	v_lshlrev_b32_e32 v206, 16, v201
	v_and_b32_e32 v207, 0xffff0000, v201
	v_pk_add_f32 v[20:21], v[20:21], v[204:205]
	v_pk_add_f32 v[22:23], v[22:23], v[206:207]
	v_lshlrev_b32_e32 v204, 16, v202
	v_and_b32_e32 v205, 0xffff0000, v202
	v_lshlrev_b32_e32 v206, 16, v203
	v_and_b32_e32 v207, 0xffff0000, v203
	v_pk_add_f32 v[16:17], v[16:17], v[204:205]
	v_pk_add_f32 v[18:19], v[18:19], v[206:207]
	global_store_dwordx4 v211, v[20:23], s[16:17] offset:512
	global_store_dwordx4 v211, v[16:19], s[16:17] offset:528
	v_add_u32_e32 v211, 0x10000, v211
	s_waitcnt vmcnt(24)
	v_lshlrev_b32_e32 v204, 16, v148
	v_and_b32_e32 v205, 0xffff0000, v148
	v_lshlrev_b32_e32 v206, 16, v149
	v_and_b32_e32 v207, 0xffff0000, v149
	v_pk_add_f32 v[12:13], v[12:13], v[204:205]
	v_pk_add_f32 v[14:15], v[14:15], v[206:207]
	v_lshlrev_b32_e32 v204, 16, v150
	v_and_b32_e32 v205, 0xffff0000, v150
	v_lshlrev_b32_e32 v206, 16, v151
	v_and_b32_e32 v207, 0xffff0000, v151
	v_pk_add_f32 v[8:9], v[8:9], v[204:205]
	v_pk_add_f32 v[10:11], v[10:11], v[206:207]
	global_store_dwordx4 v211, v[12:15], s[16:17]
	global_store_dwordx4 v211, v[8:11], s[16:17] offset:16
	v_lshlrev_b32_e32 v204, 16, v152
	v_and_b32_e32 v205, 0xffff0000, v152
	v_lshlrev_b32_e32 v206, 16, v153
	v_and_b32_e32 v207, 0xffff0000, v153
	v_pk_add_f32 v[4:5], v[4:5], v[204:205]
	v_pk_add_f32 v[6:7], v[6:7], v[206:207]
	v_lshlrev_b32_e32 v204, 16, v154
	v_and_b32_e32 v205, 0xffff0000, v154
	v_lshlrev_b32_e32 v206, 16, v155
	v_and_b32_e32 v207, 0xffff0000, v155
	v_pk_add_f32 v[0:1], v[0:1], v[204:205]
	v_pk_add_f32 v[2:3], v[2:3], v[206:207]
	global_store_dwordx4 v211, v[4:7], s[16:17] offset:512
	global_store_dwordx4 v211, v[0:3], s[16:17] offset:528
	v_add_u32_e32 v211, 0x10000, v211
	s_cbranch_vccz .LBB0_987
	s_waitcnt vmcnt(0)
	s_cmpk_gt_u32 s26, 0xff
	s_cbranch_scc1 .LBB0_1002
	s_barrier

.LBB0_1021:
	s_add_u32 s22, s20, 0x100
	s_addc_u32 s23, s21, 0
	s_add_i32 s62, 0, 0x10000
	v_add_u32_e32 v154, s62, v143
	ds_read_b128 v[138:141], v154
	ds_read_b128 v[146:149], v154 offset:1024
	ds_read_b128 v[150:153], v154 offset:2048
	ds_read_b128 v[154:157], v154 offset:3072
	s_cmp_eq_u32 s61, 40
	s_cselect_b32 s27, s9, s23
	s_cselect_b32 s26, s8, s22
	s_cselect_b32 s25, s11, s60
	s_cselect_b32 s24, s10, s39
	s_add_i32 m0, s46, 0xc000
	ds_read_b128 v[158:161], v145
	ds_read_b128 v[162:165], v145 offset:1024
	ds_read_b128 v[166:169], v145 offset:2048
	ds_read_b128 v[170:173], v145 offset:3072
	ds_read_b128 v[174:177], v145 offset:4096
	ds_read_b128 v[178:181], v145 offset:5120
	ds_read_b128 v[182:185], v145 offset:6144
	ds_read_b128 v[186:189], v145 offset:7168
	global_load_lds_dwordx4 v134, s[20:21]
	s_add_i32 m0, s46, 0xe000
	s_nop 0
	global_load_lds_dwordx4 v136, s[20:21]
	s_waitcnt lgkmcnt(8)
	s_barrier
	s_waitcnt lgkmcnt(0)
	v_mfma_f32_16x16x32_bf16 v[124:127], v[138:141], v[158:161], v[124:127]
	v_mfma_f32_16x16x32_bf16 v[120:123], v[150:153], v[158:161], v[120:123]
	v_mfma_f32_16x16x32_bf16 v[108:111], v[138:141], v[166:169], v[108:111]
	v_mfma_f32_16x16x32_bf16 v[104:107], v[150:153], v[166:169], v[104:107]
	v_mfma_f32_16x16x32_bf16 v[92:95], v[138:141], v[174:177], v[92:95]
	v_mfma_f32_16x16x32_bf16 v[88:91], v[150:153], v[174:177], v[88:91]
	v_mfma_f32_16x16x32_bf16 v[76:79], v[138:141], v[182:185], v[76:79]
	v_mfma_f32_16x16x32_bf16 v[72:75], v[150:153], v[182:185], v[72:75]
	v_mfma_f32_16x16x32_bf16 v[124:127], v[146:149], v[162:165], v[124:127]
	v_mfma_f32_16x16x32_bf16 v[120:123], v[154:157], v[162:165], v[120:123]
	v_mfma_f32_16x16x32_bf16 v[108:111], v[146:149], v[170:173], v[108:111]
	v_mfma_f32_16x16x32_bf16 v[104:107], v[154:157], v[170:173], v[104:107]
	v_mfma_f32_16x16x32_bf16 v[92:95], v[146:149], v[178:181], v[92:95]
	v_mfma_f32_16x16x32_bf16 v[88:91], v[154:157], v[178:181], v[88:91]
	v_mfma_f32_16x16x32_bf16 v[76:79], v[146:149], v[186:189], v[76:79]
	v_mfma_f32_16x16x32_bf16 v[72:75], v[154:157], v[186:189], v[72:75]
	s_barrier
	s_add_i32 s63, 0, 0x14000
	s_add_i32 s20, s62, s35
	v_add_u32_e32 v202, s63, v143
	s_add_u32 s98, s24, s40
	s_addc_u32 s99, s25, s41
	s_mov_b32 m0, s20
	ds_read_b128 v[190:193], v202
	ds_read_b128 v[194:197], v202 offset:1024
	ds_read_b128 v[198:201], v202 offset:2048
	ds_read_b128 v[202:205], v202 offset:3072
	global_load_lds_dwordx4 v208, s[24:25]
	s_add_i32 m0, s20, 0x2000
	s_nop 0
	global_load_lds_dwordx4 v128, s[24:25]
	s_barrier
	s_waitcnt lgkmcnt(0)
	v_mfma_f32_16x16x32_bf16 v[116:119], v[190:193], v[158:161], v[116:119]
	v_mfma_f32_16x16x32_bf16 v[112:115], v[198:201], v[158:161], v[112:115]
	v_mfma_f32_16x16x32_bf16 v[100:103], v[190:193], v[166:169], v[100:103]
	v_mfma_f32_16x16x32_bf16 v[96:99], v[198:201], v[166:169], v[96:99]
	v_mfma_f32_16x16x32_bf16 v[84:87], v[190:193], v[174:177], v[84:87]
	v_mfma_f32_16x16x32_bf16 v[80:83], v[198:201], v[174:177], v[80:83]
	v_mfma_f32_16x16x32_bf16 v[68:71], v[190:193], v[182:185], v[68:71]
	v_mfma_f32_16x16x32_bf16 v[64:67], v[198:201], v[182:185], v[64:67]
	v_mfma_f32_16x16x32_bf16 v[116:119], v[194:197], v[162:165], v[116:119]
	v_mfma_f32_16x16x32_bf16 v[112:115], v[202:205], v[162:165], v[112:115]
	v_mfma_f32_16x16x32_bf16 v[100:103], v[194:197], v[170:173], v[100:103]
	v_mfma_f32_16x16x32_bf16 v[96:99], v[202:205], v[170:173], v[96:99]
	v_mfma_f32_16x16x32_bf16 v[84:87], v[194:197], v[178:181], v[84:87]
	v_mfma_f32_16x16x32_bf16 v[80:83], v[202:205], v[178:181], v[80:83]
	v_mfma_f32_16x16x32_bf16 v[68:71], v[194:197], v[186:189], v[68:71]
	v_mfma_f32_16x16x32_bf16 v[64:67], v[202:205], v[186:189], v[64:67]
	s_mov_b32 m0, s46
	s_add_u32 s100, s26, s40
	s_addc_u32 s101, s27, s41
	s_barrier
	ds_read_b128 v[158:161], v145 offset:16384
	ds_read_b128 v[162:165], v145 offset:17408
	ds_read_b128 v[166:169], v145 offset:18432
	ds_read_b128 v[170:173], v145 offset:19456
	ds_read_b128 v[174:177], v145 offset:20480
	ds_read_b128 v[178:181], v145 offset:21504
	ds_read_b128 v[182:185], v145 offset:22528
	ds_read_b128 v[186:189], v145 offset:23552
	global_load_lds_dwordx4 v132, s[26:27]
	s_mov_b32 m0, s47
	s_nop 0
	global_load_lds_dwordx4 v130, s[26:27]
	s_barrier
	s_waitcnt lgkmcnt(0)
	v_mfma_f32_16x16x32_bf16 v[60:63], v[138:141], v[158:161], v[60:63]
	v_mfma_f32_16x16x32_bf16 v[56:59], v[150:153], v[158:161], v[56:59]
	v_mfma_f32_16x16x32_bf16 v[44:47], v[138:141], v[166:169], v[44:47]
	v_mfma_f32_16x16x32_bf16 v[40:43], v[150:153], v[166:169], v[40:43]
	v_mfma_f32_16x16x32_bf16 v[28:31], v[138:141], v[174:177], v[28:31]
	v_mfma_f32_16x16x32_bf16 v[24:27], v[150:153], v[174:177], v[24:27]
	v_mfma_f32_16x16x32_bf16 v[12:15], v[138:141], v[182:185], v[12:15]
	v_mfma_f32_16x16x32_bf16 v[8:11], v[150:153], v[182:185], v[8:11]
	v_mfma_f32_16x16x32_bf16 v[60:63], v[146:149], v[162:165], v[60:63]
	v_mfma_f32_16x16x32_bf16 v[56:59], v[154:157], v[162:165], v[56:59]
	v_mfma_f32_16x16x32_bf16 v[44:47], v[146:149], v[170:173], v[44:47]
	v_mfma_f32_16x16x32_bf16 v[40:43], v[154:157], v[170:173], v[40:43]
	v_mfma_f32_16x16x32_bf16 v[28:31], v[146:149], v[178:181], v[28:31]
	v_mfma_f32_16x16x32_bf16 v[24:27], v[154:157], v[178:181], v[24:27]
	v_mfma_f32_16x16x32_bf16 v[12:15], v[146:149], v[186:189], v[12:15]
	v_mfma_f32_16x16x32_bf16 v[8:11], v[154:157], v[186:189], v[8:11]
	s_barrier
	s_add_u32 s20, s24, 0xb0000
	s_addc_u32 s21, s25, 0
	s_add_i32 s62, s63, s35
	s_mov_b32 m0, s62
	s_nop 0
	global_load_lds_dwordx4 v208, s[20:21]
	s_add_i32 m0, s62, 0x2000
	s_nop 0
	global_load_lds_dwordx4 v128, s[20:21]
	s_waitcnt vmcnt(6)
	s_barrier
	v_mfma_f32_16x16x32_bf16 v[52:55], v[190:193], v[158:161], v[52:55]
	v_mfma_f32_16x16x32_bf16 v[48:51], v[198:201], v[158:161], v[48:51]
	v_mfma_f32_16x16x32_bf16 v[36:39], v[190:193], v[166:169], v[36:39]
	v_mfma_f32_16x16x32_bf16 v[32:35], v[198:201], v[166:169], v[32:35]
	v_mfma_f32_16x16x32_bf16 v[20:23], v[190:193], v[174:177], v[20:23]
	v_mfma_f32_16x16x32_bf16 v[16:19], v[198:201], v[174:177], v[16:19]
	v_mfma_f32_16x16x32_bf16 v[4:7], v[190:193], v[182:185], v[4:7]
	v_mfma_f32_16x16x32_bf16 v[0:3], v[198:201], v[182:185], v[0:3]
	v_mfma_f32_16x16x32_bf16 v[52:55], v[194:197], v[162:165], v[52:55]
	v_mfma_f32_16x16x32_bf16 v[48:51], v[202:205], v[162:165], v[48:51]
	v_mfma_f32_16x16x32_bf16 v[36:39], v[194:197], v[170:173], v[36:39]
	v_mfma_f32_16x16x32_bf16 v[32:35], v[202:205], v[170:173], v[32:35]
	v_mfma_f32_16x16x32_bf16 v[20:23], v[194:197], v[178:181], v[20:23]
	v_mfma_f32_16x16x32_bf16 v[16:19], v[202:205], v[178:181], v[16:19]
	v_mfma_f32_16x16x32_bf16 v[4:7], v[194:197], v[186:189], v[4:7]
	v_mfma_f32_16x16x32_bf16 v[0:3], v[202:205], v[186:189], v[0:3]
	s_add_i32 s62, 0, 0x18000
	v_add_u32_e32 v154, s62, v143
	s_barrier
	ds_read_b128 v[138:141], v154
	ds_read_b128 v[146:149], v154 offset:1024
	ds_read_b128 v[150:153], v154 offset:2048
	ds_read_b128 v[154:157], v154 offset:3072
	s_add_u32 s20, s26, 0xb0000
	s_addc_u32 s21, s27, 0
	s_mov_b32 m0, s50
	ds_read_b128 v[158:161], v145 offset:32768
	ds_read_b128 v[162:165], v145 offset:33792
	ds_read_b128 v[166:169], v145 offset:34816
	ds_read_b128 v[170:173], v145 offset:35840
	ds_read_b128 v[174:177], v145 offset:36864
	ds_read_b128 v[178:181], v145 offset:37888
	ds_read_b128 v[182:185], v145 offset:38912
	ds_read_b128 v[186:189], v145 offset:39936
	global_load_lds_dwordx4 v132, s[20:21]
	s_mov_b32 m0, s51
	s_nop 0
	global_load_lds_dwordx4 v130, s[20:21]
	s_waitcnt lgkmcnt(8)
	s_barrier
	s_waitcnt lgkmcnt(0)
	v_mfma_f32_16x16x32_bf16 v[124:127], v[138:141], v[158:161], v[124:127]
	v_mfma_f32_16x16x32_bf16 v[120:123], v[150:153], v[158:161], v[120:123]
	v_mfma_f32_16x16x32_bf16 v[108:111], v[138:141], v[166:169], v[108:111]
	v_mfma_f32_16x16x32_bf16 v[104:107], v[150:153], v[166:169], v[104:107]
	v_mfma_f32_16x16x32_bf16 v[92:95], v[138:141], v[174:177], v[92:95]
	v_mfma_f32_16x16x32_bf16 v[88:91], v[150:153], v[174:177], v[88:91]
	v_mfma_f32_16x16x32_bf16 v[76:79], v[138:141], v[182:185], v[76:79]
	v_mfma_f32_16x16x32_bf16 v[72:75], v[150:153], v[182:185], v[72:75]
	v_mfma_f32_16x16x32_bf16 v[124:127], v[146:149], v[162:165], v[124:127]
	v_mfma_f32_16x16x32_bf16 v[120:123], v[154:157], v[162:165], v[120:123]
	v_mfma_f32_16x16x32_bf16 v[108:111], v[146:149], v[170:173], v[108:111]
	v_mfma_f32_16x16x32_bf16 v[104:107], v[154:157], v[170:173], v[104:107]
	v_mfma_f32_16x16x32_bf16 v[92:95], v[146:149], v[178:181], v[92:95]
	v_mfma_f32_16x16x32_bf16 v[88:91], v[154:157], v[178:181], v[88:91]
	v_mfma_f32_16x16x32_bf16 v[76:79], v[146:149], v[186:189], v[76:79]
	v_mfma_f32_16x16x32_bf16 v[72:75], v[154:157], v[186:189], v[72:75]
	s_barrier
	s_add_i32 s26, 0, 0x1c000
	s_add_i32 s20, s62, s35
	v_add_u32_e32 v202, s26, v143
	s_mov_b32 m0, s20
	ds_read_b128 v[190:193], v202
	ds_read_b128 v[194:197], v202 offset:1024
	ds_read_b128 v[198:201], v202 offset:2048
	ds_read_b128 v[202:205], v202 offset:3072
	global_load_lds_dwordx4 v208, s[98:99]
	s_add_i32 m0, s20, 0x2000
	s_nop 0
	global_load_lds_dwordx4 v128, s[98:99]
	s_barrier
	s_waitcnt lgkmcnt(0)
	v_mfma_f32_16x16x32_bf16 v[116:119], v[190:193], v[158:161], v[116:119]
	v_mfma_f32_16x16x32_bf16 v[112:115], v[198:201], v[158:161], v[112:115]
	v_mfma_f32_16x16x32_bf16 v[100:103], v[190:193], v[166:169], v[100:103]
	v_mfma_f32_16x16x32_bf16 v[96:99], v[198:201], v[166:169], v[96:99]
	v_mfma_f32_16x16x32_bf16 v[84:87], v[190:193], v[174:177], v[84:87]
	v_mfma_f32_16x16x32_bf16 v[80:83], v[198:201], v[174:177], v[80:83]
	v_mfma_f32_16x16x32_bf16 v[68:71], v[190:193], v[182:185], v[68:71]
	v_mfma_f32_16x16x32_bf16 v[64:67], v[198:201], v[182:185], v[64:67]
	v_mfma_f32_16x16x32_bf16 v[116:119], v[194:197], v[162:165], v[116:119]
	v_mfma_f32_16x16x32_bf16 v[112:115], v[202:205], v[162:165], v[112:115]
	v_mfma_f32_16x16x32_bf16 v[100:103], v[194:197], v[170:173], v[100:103]
	v_mfma_f32_16x16x32_bf16 v[96:99], v[202:205], v[170:173], v[96:99]
	v_mfma_f32_16x16x32_bf16 v[84:87], v[194:197], v[178:181], v[84:87]
	v_mfma_f32_16x16x32_bf16 v[80:83], v[202:205], v[178:181], v[80:83]
	v_mfma_f32_16x16x32_bf16 v[68:71], v[194:197], v[186:189], v[68:71]
	v_mfma_f32_16x16x32_bf16 v[64:67], v[202:205], v[186:189], v[64:67]
	s_mov_b32 m0, s53
	s_barrier
	ds_read_b128 v[158:161], v145 offset:49152
	ds_read_b128 v[162:165], v145 offset:50176
	ds_read_b128 v[166:169], v145 offset:51200
	ds_read_b128 v[170:173], v145 offset:52224
	ds_read_b128 v[174:177], v145 offset:53248
	ds_read_b128 v[178:181], v145 offset:54272
	ds_read_b128 v[182:185], v145 offset:55296
	ds_read_b128 v[186:189], v145 offset:56320
	global_load_lds_dwordx4 v132, s[100:101]
	s_mov_b32 m0, s56
	s_nop 0
	global_load_lds_dwordx4 v130, s[100:101]
	s_barrier
	s_waitcnt lgkmcnt(0)
	v_mfma_f32_16x16x32_bf16 v[60:63], v[138:141], v[158:161], v[60:63]
	v_mfma_f32_16x16x32_bf16 v[56:59], v[150:153], v[158:161], v[56:59]
	v_mfma_f32_16x16x32_bf16 v[44:47], v[138:141], v[166:169], v[44:47]
	v_mfma_f32_16x16x32_bf16 v[40:43], v[150:153], v[166:169], v[40:43]
	v_mfma_f32_16x16x32_bf16 v[28:31], v[138:141], v[174:177], v[28:31]
	v_mfma_f32_16x16x32_bf16 v[24:27], v[150:153], v[174:177], v[24:27]
	v_mfma_f32_16x16x32_bf16 v[12:15], v[138:141], v[182:185], v[12:15]
	v_mfma_f32_16x16x32_bf16 v[8:11], v[150:153], v[182:185], v[8:11]
	v_mfma_f32_16x16x32_bf16 v[60:63], v[146:149], v[162:165], v[60:63]
	v_mfma_f32_16x16x32_bf16 v[56:59], v[154:157], v[162:165], v[56:59]
	v_mfma_f32_16x16x32_bf16 v[44:47], v[146:149], v[170:173], v[44:47]
	v_mfma_f32_16x16x32_bf16 v[40:43], v[154:157], v[170:173], v[40:43]
	v_mfma_f32_16x16x32_bf16 v[28:31], v[146:149], v[178:181], v[28:31]
	v_mfma_f32_16x16x32_bf16 v[24:27], v[154:157], v[178:181], v[24:27]
	v_mfma_f32_16x16x32_bf16 v[12:15], v[146:149], v[186:189], v[12:15]
	v_mfma_f32_16x16x32_bf16 v[8:11], v[154:157], v[186:189], v[8:11]
	s_barrier
	s_add_u32 s20, s24, 0xb0080
	s_addc_u32 s21, s25, 0
	s_add_i32 s24, s26, s35
	s_mov_b32 m0, s24
	s_nop 0
	global_load_lds_dwordx4 v208, s[20:21]
	s_add_i32 m0, s24, 0x2000
	s_nop 0
	global_load_lds_dwordx4 v128, s[20:21]
	s_waitcnt vmcnt(6)
	s_barrier
	v_mfma_f32_16x16x32_bf16 v[52:55], v[190:193], v[158:161], v[52:55]
	v_mfma_f32_16x16x32_bf16 v[48:51], v[198:201], v[158:161], v[48:51]
	v_mfma_f32_16x16x32_bf16 v[36:39], v[190:193], v[166:169], v[36:39]
	v_mfma_f32_16x16x32_bf16 v[32:35], v[198:201], v[166:169], v[32:35]
	v_mfma_f32_16x16x32_bf16 v[20:23], v[190:193], v[174:177], v[20:23]
	v_mfma_f32_16x16x32_bf16 v[16:19], v[198:201], v[174:177], v[16:19]
	v_mfma_f32_16x16x32_bf16 v[4:7], v[190:193], v[182:185], v[4:7]
	v_mfma_f32_16x16x32_bf16 v[0:3], v[198:201], v[182:185], v[0:3]
	v_mfma_f32_16x16x32_bf16 v[52:55], v[194:197], v[162:165], v[52:55]
	v_mfma_f32_16x16x32_bf16 v[48:51], v[202:205], v[162:165], v[48:51]
	v_mfma_f32_16x16x32_bf16 v[36:39], v[194:197], v[170:173], v[36:39]
	v_mfma_f32_16x16x32_bf16 v[32:35], v[202:205], v[170:173], v[32:35]
	v_mfma_f32_16x16x32_bf16 v[20:23], v[194:197], v[178:181], v[20:23]
	v_mfma_f32_16x16x32_bf16 v[16:19], v[202:205], v[178:181], v[16:19]
	v_mfma_f32_16x16x32_bf16 v[4:7], v[194:197], v[186:189], v[4:7]
	v_mfma_f32_16x16x32_bf16 v[0:3], v[202:205], v[186:189], v[0:3]
	s_add_i32 s61, s61, 2
	s_add_u32 s39, s39, 0x100
	s_addc_u32 s60, s60, 0
	s_cmp_gt_u32 s61, 41
	s_mov_b64 s[20:21], s[22:23]
	s_barrier
	s_cbranch_scc0 .LBB0_1021
	v_lshl_add_u32 v140, s38, 8, v142
	v_lshl_or_b32 v141, s36, 8, v144
	s_lshl_b32 s20, s36, 2
	s_ashr_i32 s21, s20, 31
	s_lshl_b32 s36, s52, 2
	v_lshlrev_b32_e32 v206, 11, v140
	v_lshl_add_u32 v206, v141, 1, v206
	v_lshl_add_u32 v210, v140, 6, s36
	v_lshl_add_u32 v210, s20, 2, v210
	v_mov_b32_e32 v207, v206
	global_load_dwordx4 v[146:149], v206, s[14:15]
	global_load_dwordx4 v[150:153], v206, s[14:15] offset:256
	v_add_u32_e32 v206, 0x8000, v206
	global_load_dwordx4 v[154:157], v206, s[14:15]
	global_load_dwordx4 v[158:161], v206, s[14:15] offset:256
	v_add_u32_e32 v206, 0x8000, v206
	global_load_dwordx4 v[162:165], v206, s[14:15]
	global_load_dwordx4 v[166:169], v206, s[14:15] offset:256
	v_add_u32_e32 v206, 0x8000, v206
	global_load_dwordx4 v[170:173], v206, s[14:15]
	global_load_dwordx4 v[174:177], v206, s[14:15] offset:256
	v_add_u32_e32 v206, 0x28000, v206
	global_load_dwordx4 v[178:181], v206, s[14:15]
	global_load_dwordx4 v[182:185], v206, s[14:15] offset:256
	v_add_u32_e32 v206, 0x8000, v206
	global_load_dwordx4 v[186:189], v206, s[14:15]
	global_load_dwordx4 v[190:193], v206, s[14:15] offset:256
	v_add_u32_e32 v206, 0x8000, v206
	global_load_dwordx4 v[194:197], v206, s[14:15]
	global_load_dwordx4 v[198:201], v206, s[14:15] offset:256
	v_add_u32_e32 v206, 0x8000, v206
	s_waitcnt vmcnt(12)
	v_lshlrev_b32_e32 v202, 16, v146
	v_and_b32_e32 v203, 0xffff0000, v146
	v_lshlrev_b32_e32 v204, 16, v147
	v_and_b32_e32 v205, 0xffff0000, v147
	v_pk_add_f32 v[124:125], v[124:125], v[202:203]
	v_pk_add_f32 v[126:127], v[126:127], v[204:205]
	v_lshlrev_b32_e32 v202, 16, v148
	v_and_b32_e32 v203, 0xffff0000, v148
	v_lshlrev_b32_e32 v204, 16, v149
	v_and_b32_e32 v205, 0xffff0000, v149
	v_pk_add_f32 v[120:121], v[120:121], v[202:203]
	v_pk_add_f32 v[122:123], v[122:123], v[204:205]
	v_cvt_pk_bf16_f32 v146, v124, v125
	v_cvt_pk_bf16_f32 v147, v126, v127
	v_cvt_pk_bf16_f32 v148, v120, v121
	v_cvt_pk_bf16_f32 v149, v122, v123
	v_pk_mul_f32 v[138:139], v[124:125], v[124:125]
	global_store_dwordx4 v207, v[146:149], s[14:15]
	v_pk_fma_f32 v[138:139], v[126:127], v[126:127], v[138:139]
	v_pk_fma_f32 v[138:139], v[120:121], v[120:121], v[138:139]
	v_pk_fma_f32 v[138:139], v[122:123], v[122:123], v[138:139]
	v_lshlrev_b32_e32 v202, 16, v150
	v_and_b32_e32 v203, 0xffff0000, v150
	v_lshlrev_b32_e32 v204, 16, v151
	v_and_b32_e32 v205, 0xffff0000, v151
	v_pk_add_f32 v[116:117], v[116:117], v[202:203]
	v_pk_add_f32 v[118:119], v[118:119], v[204:205]
	v_lshlrev_b32_e32 v202, 16, v152
	v_and_b32_e32 v203, 0xffff0000, v152
	v_lshlrev_b32_e32 v204, 16, v153
	v_and_b32_e32 v205, 0xffff0000, v153
	v_pk_add_f32 v[112:113], v[112:113], v[202:203]
	v_pk_add_f32 v[114:115], v[114:115], v[204:205]
	v_cvt_pk_bf16_f32 v150, v116, v117
	v_cvt_pk_bf16_f32 v151, v118, v119
	v_cvt_pk_bf16_f32 v152, v112, v113
	v_cvt_pk_bf16_f32 v153, v114, v115
	v_pk_fma_f32 v[138:139], v[116:117], v[116:117], v[138:139]
	global_store_dwordx4 v207, v[150:153], s[14:15] offset:256
	v_pk_fma_f32 v[138:139], v[118:119], v[118:119], v[138:139]
	v_pk_fma_f32 v[138:139], v[112:113], v[112:113], v[138:139]
	v_pk_fma_f32 v[138:139], v[114:115], v[114:115], v[138:139]
	v_add_f32_e32 v214, v138, v139
	v_add_u32_e32 v207, 0x8000, v207
	v_mov_b32_e32 v215, v214
	s_nop 1
	v_permlane16_swap_b32_e32 v214, v215
	s_nop 0
	v_add_f32_e32 v214, v214, v215
	v_mov_b32_e32 v215, v214
	s_nop 1
	v_permlane32_swap_b32_e32 v214, v215
	s_nop 0
	v_add_f32_e32 v214, v214, v215
	s_and_saveexec_b64 s[22:23], s[4:5]
	global_store_dword v210, v214, s[16:17]
	s_mov_b64 exec, s[22:23]
	global_load_dwordx4 v[146:149], v206, s[14:15]
	global_load_dwordx4 v[150:153], v206, s[14:15] offset:256
	s_waitcnt vmcnt(15)
	v_lshlrev_b32_e32 v202, 16, v154
	v_and_b32_e32 v203, 0xffff0000, v154
	v_lshlrev_b32_e32 v204, 16, v155
	v_and_b32_e32 v205, 0xffff0000, v155
	v_pk_add_f32 v[108:109], v[108:109], v[202:203]
	v_pk_add_f32 v[110:111], v[110:111], v[204:205]
	v_lshlrev_b32_e32 v202, 16, v156
	v_and_b32_e32 v203, 0xffff0000, v156
	v_lshlrev_b32_e32 v204, 16, v157
	v_and_b32_e32 v205, 0xffff0000, v157
	v_pk_add_f32 v[104:105], v[104:105], v[202:203]
	v_pk_add_f32 v[106:107], v[106:107], v[204:205]
	v_cvt_pk_bf16_f32 v154, v108, v109
	v_cvt_pk_bf16_f32 v155, v110, v111
	v_cvt_pk_bf16_f32 v156, v104, v105
	v_cvt_pk_bf16_f32 v157, v106, v107
	v_pk_mul_f32 v[138:139], v[108:109], v[108:109]
	global_store_dwordx4 v207, v[154:157], s[14:15]
	v_pk_fma_f32 v[138:139], v[110:111], v[110:111], v[138:139]
	v_pk_fma_f32 v[138:139], v[104:105], v[104:105], v[138:139]
	v_pk_fma_f32 v[138:139], v[106:107], v[106:107], v[138:139]
	v_lshlrev_b32_e32 v202, 16, v158
	v_and_b32_e32 v203, 0xffff0000, v158
	v_lshlrev_b32_e32 v204, 16, v159
	v_and_b32_e32 v205, 0xffff0000, v159
	v_pk_add_f32 v[100:101], v[100:101], v[202:203]
	v_pk_add_f32 v[102:103], v[102:103], v[204:205]
	v_lshlrev_b32_e32 v202, 16, v160
	v_and_b32_e32 v203, 0xffff0000, v160
	v_lshlrev_b32_e32 v204, 16, v161
	v_and_b32_e32 v205, 0xffff0000, v161
	v_pk_add_f32 v[96:97], v[96:97], v[202:203]
	v_pk_add_f32 v[98:99], v[98:99], v[204:205]
	v_cvt_pk_bf16_f32 v158, v100, v101
	v_cvt_pk_bf16_f32 v159, v102, v103
	v_cvt_pk_bf16_f32 v160, v96, v97
	v_cvt_pk_bf16_f32 v161, v98, v99
	v_pk_fma_f32 v[138:139], v[100:101], v[100:101], v[138:139]
	global_store_dwordx4 v207, v[158:161], s[14:15] offset:256
	v_pk_fma_f32 v[138:139], v[102:103], v[102:103], v[138:139]
	v_pk_fma_f32 v[138:139], v[96:97], v[96:97], v[138:139]
	v_pk_fma_f32 v[138:139], v[98:99], v[98:99], v[138:139]
	v_add_f32_e32 v214, v138, v139
	v_add_u32_e32 v207, 0x8000, v207
	v_mov_b32_e32 v215, v214
	s_nop 1
	v_permlane16_swap_b32_e32 v214, v215
	s_nop 0
	v_add_f32_e32 v214, v214, v215
	v_mov_b32_e32 v215, v214
	s_nop 1
	v_permlane32_swap_b32_e32 v214, v215
	s_nop 0
	v_add_f32_e32 v214, v214, v215
	s_and_saveexec_b64 s[22:23], s[4:5]
	global_store_dword v210, v214, s[16:17] offset:1024
	s_mov_b64 exec, s[22:23]
	s_waitcnt vmcnt(16)
	v_lshlrev_b32_e32 v202, 16, v162
	v_and_b32_e32 v203, 0xffff0000, v162
	v_lshlrev_b32_e32 v204, 16, v163
	v_and_b32_e32 v205, 0xffff0000, v163
	v_pk_add_f32 v[92:93], v[92:93], v[202:203]
	v_pk_add_f32 v[94:95], v[94:95], v[204:205]
	v_lshlrev_b32_e32 v202, 16, v164
	v_and_b32_e32 v203, 0xffff0000, v164
	v_lshlrev_b32_e32 v204, 16, v165
	v_and_b32_e32 v205, 0xffff0000, v165
	v_pk_add_f32 v[88:89], v[88:89], v[202:203]
	v_pk_add_f32 v[90:91], v[90:91], v[204:205]
	v_cvt_pk_bf16_f32 v162, v92, v93
	v_cvt_pk_bf16_f32 v163, v94, v95
	v_cvt_pk_bf16_f32 v164, v88, v89
	v_cvt_pk_bf16_f32 v165, v90, v91
	v_pk_mul_f32 v[138:139], v[92:93], v[92:93]
	global_store_dwordx4 v207, v[162:165], s[14:15]
	v_pk_fma_f32 v[138:139], v[94:95], v[94:95], v[138:139]
	v_pk_fma_f32 v[138:139], v[88:89], v[88:89], v[138:139]
	v_pk_fma_f32 v[138:139], v[90:91], v[90:91], v[138:139]
	v_lshlrev_b32_e32 v202, 16, v166
	v_and_b32_e32 v203, 0xffff0000, v166
	v_lshlrev_b32_e32 v204, 16, v167
	v_and_b32_e32 v205, 0xffff0000, v167
	v_pk_add_f32 v[84:85], v[84:85], v[202:203]
	v_pk_add_f32 v[86:87], v[86:87], v[204:205]
	v_lshlrev_b32_e32 v202, 16, v168
	v_and_b32_e32 v203, 0xffff0000, v168
	v_lshlrev_b32_e32 v204, 16, v169
	v_and_b32_e32 v205, 0xffff0000, v169
	v_pk_add_f32 v[80:81], v[80:81], v[202:203]
	v_pk_add_f32 v[82:83], v[82:83], v[204:205]
	v_cvt_pk_bf16_f32 v166, v84, v85
	v_cvt_pk_bf16_f32 v167, v86, v87
	v_cvt_pk_bf16_f32 v168, v80, v81
	v_cvt_pk_bf16_f32 v169, v82, v83
	v_pk_fma_f32 v[138:139], v[84:85], v[84:85], v[138:139]
	global_store_dwordx4 v207, v[166:169], s[14:15] offset:256
	v_pk_fma_f32 v[138:139], v[86:87], v[86:87], v[138:139]
	v_pk_fma_f32 v[138:139], v[80:81], v[80:81], v[138:139]
	v_pk_fma_f32 v[138:139], v[82:83], v[82:83], v[138:139]
	v_add_f32_e32 v214, v138, v139
	v_add_u32_e32 v207, 0x8000, v207
	v_mov_b32_e32 v215, v214
	s_nop 1
	v_permlane16_swap_b32_e32 v214, v215
	s_nop 0
	v_add_f32_e32 v214, v214, v215
	v_mov_b32_e32 v215, v214
	s_nop 1
	v_permlane32_swap_b32_e32 v214, v215
	s_nop 0
	v_add_f32_e32 v214, v214, v215
	s_and_saveexec_b64 s[22:23], s[4:5]
	global_store_dword v210, v214, s[16:17] offset:2048
	s_mov_b64 exec, s[22:23]
	s_waitcnt vmcnt(17)
	v_lshlrev_b32_e32 v202, 16, v170
	v_and_b32_e32 v203, 0xffff0000, v170
	v_lshlrev_b32_e32 v204, 16, v171
	v_and_b32_e32 v205, 0xffff0000, v171
	v_pk_add_f32 v[76:77], v[76:77], v[202:203]
	v_pk_add_f32 v[78:79], v[78:79], v[204:205]
	v_lshlrev_b32_e32 v202, 16, v172
	v_and_b32_e32 v203, 0xffff0000, v172
	v_lshlrev_b32_e32 v204, 16, v173
	v_and_b32_e32 v205, 0xffff0000, v173
	v_pk_add_f32 v[72:73], v[72:73], v[202:203]
	v_pk_add_f32 v[74:75], v[74:75], v[204:205]
	v_cvt_pk_bf16_f32 v170, v76, v77
	v_cvt_pk_bf16_f32 v171, v78, v79
	v_cvt_pk_bf16_f32 v172, v72, v73
	v_cvt_pk_bf16_f32 v173, v74, v75
	v_pk_mul_f32 v[138:139], v[76:77], v[76:77]
	global_store_dwordx4 v207, v[170:173], s[14:15]
	v_pk_fma_f32 v[138:139], v[78:79], v[78:79], v[138:139]
	v_pk_fma_f32 v[138:139], v[72:73], v[72:73], v[138:139]
	v_pk_fma_f32 v[138:139], v[74:75], v[74:75], v[138:139]
	v_lshlrev_b32_e32 v202, 16, v174
	v_and_b32_e32 v203, 0xffff0000, v174
	v_lshlrev_b32_e32 v204, 16, v175
	v_and_b32_e32 v205, 0xffff0000, v175
	v_pk_add_f32 v[68:69], v[68:69], v[202:203]
	v_pk_add_f32 v[70:71], v[70:71], v[204:205]
	v_lshlrev_b32_e32 v202, 16, v176
	v_and_b32_e32 v203, 0xffff0000, v176
	v_lshlrev_b32_e32 v204, 16, v177
	v_and_b32_e32 v205, 0xffff0000, v177
	v_pk_add_f32 v[64:65], v[64:65], v[202:203]
	v_pk_add_f32 v[66:67], v[66:67], v[204:205]
	v_cvt_pk_bf16_f32 v174, v68, v69
	v_cvt_pk_bf16_f32 v175, v70, v71
	v_cvt_pk_bf16_f32 v176, v64, v65
	v_cvt_pk_bf16_f32 v177, v66, v67
	v_pk_fma_f32 v[138:139], v[68:69], v[68:69], v[138:139]
	global_store_dwordx4 v207, v[174:177], s[14:15] offset:256
	v_pk_fma_f32 v[138:139], v[70:71], v[70:71], v[138:139]
	v_pk_fma_f32 v[138:139], v[64:65], v[64:65], v[138:139]
	v_pk_fma_f32 v[138:139], v[66:67], v[66:67], v[138:139]
	v_add_f32_e32 v214, v138, v139
	v_add_u32_e32 v207, 0x28000, v207
	v_mov_b32_e32 v215, v214
	s_nop 1
	v_permlane16_swap_b32_e32 v214, v215
	s_nop 0
	v_add_f32_e32 v214, v214, v215
	v_mov_b32_e32 v215, v214
	s_nop 1
	v_permlane32_swap_b32_e32 v214, v215
	s_nop 0
	v_add_f32_e32 v214, v214, v215
	s_and_saveexec_b64 s[22:23], s[4:5]
	global_store_dword v210, v214, s[16:17] offset:3072
	s_mov_b64 exec, s[22:23]
	v_add_u32_e32 v210, 0x2000, v210
	s_waitcnt vmcnt(18)
	v_lshlrev_b32_e32 v202, 16, v178
	v_and_b32_e32 v203, 0xffff0000, v178
	v_lshlrev_b32_e32 v204, 16, v179
	v_and_b32_e32 v205, 0xffff0000, v179
	v_pk_add_f32 v[60:61], v[60:61], v[202:203]
	v_pk_add_f32 v[62:63], v[62:63], v[204:205]
	v_lshlrev_b32_e32 v202, 16, v180
	v_and_b32_e32 v203, 0xffff0000, v180
	v_lshlrev_b32_e32 v204, 16, v181
	v_and_b32_e32 v205, 0xffff0000, v181
	v_pk_add_f32 v[56:57], v[56:57], v[202:203]
	v_pk_add_f32 v[58:59], v[58:59], v[204:205]
	v_cvt_pk_bf16_f32 v178, v60, v61
	v_cvt_pk_bf16_f32 v179, v62, v63
	v_cvt_pk_bf16_f32 v180, v56, v57
	v_cvt_pk_bf16_f32 v181, v58, v59
	v_pk_mul_f32 v[138:139], v[60:61], v[60:61]
	global_store_dwordx4 v207, v[178:181], s[14:15]
	v_pk_fma_f32 v[138:139], v[62:63], v[62:63], v[138:139]
	v_pk_fma_f32 v[138:139], v[56:57], v[56:57], v[138:139]
	v_pk_fma_f32 v[138:139], v[58:59], v[58:59], v[138:139]
	v_lshlrev_b32_e32 v202, 16, v182
	v_and_b32_e32 v203, 0xffff0000, v182
	v_lshlrev_b32_e32 v204, 16, v183
	v_and_b32_e32 v205, 0xffff0000, v183
	v_pk_add_f32 v[52:53], v[52:53], v[202:203]
	v_pk_add_f32 v[54:55], v[54:55], v[204:205]
	v_lshlrev_b32_e32 v202, 16, v184
	v_and_b32_e32 v203, 0xffff0000, v184
	v_lshlrev_b32_e32 v204, 16, v185
	v_and_b32_e32 v205, 0xffff0000, v185
	v_pk_add_f32 v[48:49], v[48:49], v[202:203]
	v_pk_add_f32 v[50:51], v[50:51], v[204:205]
	v_cvt_pk_bf16_f32 v182, v52, v53
	v_cvt_pk_bf16_f32 v183, v54, v55
	v_cvt_pk_bf16_f32 v184, v48, v49
	v_cvt_pk_bf16_f32 v185, v50, v51
	v_pk_fma_f32 v[138:139], v[52:53], v[52:53], v[138:139]
	global_store_dwordx4 v207, v[182:185], s[14:15] offset:256
	v_pk_fma_f32 v[138:139], v[54:55], v[54:55], v[138:139]
	v_pk_fma_f32 v[138:139], v[48:49], v[48:49], v[138:139]
	v_pk_fma_f32 v[138:139], v[50:51], v[50:51], v[138:139]
	v_add_f32_e32 v214, v138, v139
	v_add_u32_e32 v207, 0x8000, v207
	v_mov_b32_e32 v215, v214
	s_nop 1
	v_permlane16_swap_b32_e32 v214, v215
	s_nop 0
	v_add_f32_e32 v214, v214, v215
	v_mov_b32_e32 v215, v214
	s_nop 1
	v_permlane32_swap_b32_e32 v214, v215
	s_nop 0
	v_add_f32_e32 v214, v214, v215
	s_and_saveexec_b64 s[22:23], s[4:5]
	global_store_dword v210, v214, s[16:17]
	s_mov_b64 exec, s[22:23]
	s_waitcnt vmcnt(19)
	v_lshlrev_b32_e32 v202, 16, v186
	v_and_b32_e32 v203, 0xffff0000, v186
	v_lshlrev_b32_e32 v204, 16, v187
	v_and_b32_e32 v205, 0xffff0000, v187
	v_pk_add_f32 v[44:45], v[44:45], v[202:203]
	v_pk_add_f32 v[46:47], v[46:47], v[204:205]
	v_lshlrev_b32_e32 v202, 16, v188
	v_and_b32_e32 v203, 0xffff0000, v188
	v_lshlrev_b32_e32 v204, 16, v189
	v_and_b32_e32 v205, 0xffff0000, v189
	v_pk_add_f32 v[40:41], v[40:41], v[202:203]
	v_pk_add_f32 v[42:43], v[42:43], v[204:205]
	v_cvt_pk_bf16_f32 v186, v44, v45
	v_cvt_pk_bf16_f32 v187, v46, v47
	v_cvt_pk_bf16_f32 v188, v40, v41
	v_cvt_pk_bf16_f32 v189, v42, v43
	v_pk_mul_f32 v[138:139], v[44:45], v[44:45]
	global_store_dwordx4 v207, v[186:189], s[14:15]
	v_pk_fma_f32 v[138:139], v[46:47], v[46:47], v[138:139]
	v_pk_fma_f32 v[138:139], v[40:41], v[40:41], v[138:139]
	v_pk_fma_f32 v[138:139], v[42:43], v[42:43], v[138:139]
	v_lshlrev_b32_e32 v202, 16, v190
	v_and_b32_e32 v203, 0xffff0000, v190
	v_lshlrev_b32_e32 v204, 16, v191
	v_and_b32_e32 v205, 0xffff0000, v191
	v_pk_add_f32 v[36:37], v[36:37], v[202:203]
	v_pk_add_f32 v[38:39], v[38:39], v[204:205]
	v_lshlrev_b32_e32 v202, 16, v192
	v_and_b32_e32 v203, 0xffff0000, v192
	v_lshlrev_b32_e32 v204, 16, v193
	v_and_b32_e32 v205, 0xffff0000, v193
	v_pk_add_f32 v[32:33], v[32:33], v[202:203]
	v_pk_add_f32 v[34:35], v[34:35], v[204:205]
	v_cvt_pk_bf16_f32 v190, v36, v37
	v_cvt_pk_bf16_f32 v191, v38, v39
	v_cvt_pk_bf16_f32 v192, v32, v33
	v_cvt_pk_bf16_f32 v193, v34, v35
	v_pk_fma_f32 v[138:139], v[36:37], v[36:37], v[138:139]
	global_store_dwordx4 v207, v[190:193], s[14:15] offset:256
	v_pk_fma_f32 v[138:139], v[38:39], v[38:39], v[138:139]
	v_pk_fma_f32 v[138:139], v[32:33], v[32:33], v[138:139]
	v_pk_fma_f32 v[138:139], v[34:35], v[34:35], v[138:139]
	v_add_f32_e32 v214, v138, v139
	v_add_u32_e32 v207, 0x8000, v207
	v_mov_b32_e32 v215, v214
	s_nop 1
	v_permlane16_swap_b32_e32 v214, v215
	s_nop 0
	v_add_f32_e32 v214, v214, v215
	v_mov_b32_e32 v215, v214
	s_nop 1
	v_permlane32_swap_b32_e32 v214, v215
	s_nop 0
	v_add_f32_e32 v214, v214, v215
	s_and_saveexec_b64 s[22:23], s[4:5]
	global_store_dword v210, v214, s[16:17] offset:1024
	s_mov_b64 exec, s[22:23]
	s_waitcnt vmcnt(20)
	v_lshlrev_b32_e32 v202, 16, v194
	v_and_b32_e32 v203, 0xffff0000, v194
	v_lshlrev_b32_e32 v204, 16, v195
	v_and_b32_e32 v205, 0xffff0000, v195
	v_pk_add_f32 v[28:29], v[28:29], v[202:203]
	v_pk_add_f32 v[30:31], v[30:31], v[204:205]
	v_lshlrev_b32_e32 v202, 16, v196
	v_and_b32_e32 v203, 0xffff0000, v196
	v_lshlrev_b32_e32 v204, 16, v197
	v_and_b32_e32 v205, 0xffff0000, v197
	v_pk_add_f32 v[24:25], v[24:25], v[202:203]
	v_pk_add_f32 v[26:27], v[26:27], v[204:205]
	v_cvt_pk_bf16_f32 v194, v28, v29
	v_cvt_pk_bf16_f32 v195, v30, v31
	v_cvt_pk_bf16_f32 v196, v24, v25
	v_cvt_pk_bf16_f32 v197, v26, v27
	v_pk_mul_f32 v[138:139], v[28:29], v[28:29]
	global_store_dwordx4 v207, v[194:197], s[14:15]
	v_pk_fma_f32 v[138:139], v[30:31], v[30:31], v[138:139]
	v_pk_fma_f32 v[138:139], v[24:25], v[24:25], v[138:139]
	v_pk_fma_f32 v[138:139], v[26:27], v[26:27], v[138:139]
	v_lshlrev_b32_e32 v202, 16, v198
	v_and_b32_e32 v203, 0xffff0000, v198
	v_lshlrev_b32_e32 v204, 16, v199
	v_and_b32_e32 v205, 0xffff0000, v199
	v_pk_add_f32 v[20:21], v[20:21], v[202:203]
	v_pk_add_f32 v[22:23], v[22:23], v[204:205]
	v_lshlrev_b32_e32 v202, 16, v200
	v_and_b32_e32 v203, 0xffff0000, v200
	v_lshlrev_b32_e32 v204, 16, v201
	v_and_b32_e32 v205, 0xffff0000, v201
	v_pk_add_f32 v[16:17], v[16:17], v[202:203]
	v_pk_add_f32 v[18:19], v[18:19], v[204:205]
	v_cvt_pk_bf16_f32 v198, v20, v21
	v_cvt_pk_bf16_f32 v199, v22, v23
	v_cvt_pk_bf16_f32 v200, v16, v17
	v_cvt_pk_bf16_f32 v201, v18, v19
	v_pk_fma_f32 v[138:139], v[20:21], v[20:21], v[138:139]
	global_store_dwordx4 v207, v[198:201], s[14:15] offset:256
	v_pk_fma_f32 v[138:139], v[22:23], v[22:23], v[138:139]
	v_pk_fma_f32 v[138:139], v[16:17], v[16:17], v[138:139]
	v_pk_fma_f32 v[138:139], v[18:19], v[18:19], v[138:139]
	v_add_f32_e32 v214, v138, v139
	v_add_u32_e32 v207, 0x8000, v207
	v_mov_b32_e32 v215, v214
	s_nop 1
	v_permlane16_swap_b32_e32 v214, v215
	s_nop 0
	v_add_f32_e32 v214, v214, v215
	v_mov_b32_e32 v215, v214
	s_nop 1
	v_permlane32_swap_b32_e32 v214, v215
	s_nop 0
	v_add_f32_e32 v214, v214, v215
	s_and_saveexec_b64 s[22:23], s[4:5]
	global_store_dword v210, v214, s[16:17] offset:2048
	s_mov_b64 exec, s[22:23]
	s_waitcnt vmcnt(18)
	v_lshlrev_b32_e32 v202, 16, v146
	v_and_b32_e32 v203, 0xffff0000, v146
	v_lshlrev_b32_e32 v204, 16, v147
	v_and_b32_e32 v205, 0xffff0000, v147
	v_pk_add_f32 v[12:13], v[12:13], v[202:203]
	v_pk_add_f32 v[14:15], v[14:15], v[204:205]
	v_lshlrev_b32_e32 v202, 16, v148
	v_and_b32_e32 v203, 0xffff0000, v148
	v_lshlrev_b32_e32 v204, 16, v149
	v_and_b32_e32 v205, 0xffff0000, v149
	v_pk_add_f32 v[8:9], v[8:9], v[202:203]
	v_pk_add_f32 v[10:11], v[10:11], v[204:205]
	v_cvt_pk_bf16_f32 v146, v12, v13
	v_cvt_pk_bf16_f32 v147, v14, v15
	v_cvt_pk_bf16_f32 v148, v8, v9
	v_cvt_pk_bf16_f32 v149, v10, v11
	v_pk_mul_f32 v[138:139], v[12:13], v[12:13]
	global_store_dwordx4 v207, v[146:149], s[14:15]
	v_pk_fma_f32 v[138:139], v[14:15], v[14:15], v[138:139]
	v_pk_fma_f32 v[138:139], v[8:9], v[8:9], v[138:139]
	v_pk_fma_f32 v[138:139], v[10:11], v[10:11], v[138:139]
	v_lshlrev_b32_e32 v202, 16, v150
	v_and_b32_e32 v203, 0xffff0000, v150
	v_lshlrev_b32_e32 v204, 16, v151
	v_and_b32_e32 v205, 0xffff0000, v151
	v_pk_add_f32 v[4:5], v[4:5], v[202:203]
	v_pk_add_f32 v[6:7], v[6:7], v[204:205]
	v_lshlrev_b32_e32 v202, 16, v152
	v_and_b32_e32 v203, 0xffff0000, v152
	v_lshlrev_b32_e32 v204, 16, v153
	v_and_b32_e32 v205, 0xffff0000, v153
	v_pk_add_f32 v[0:1], v[0:1], v[202:203]
	v_pk_add_f32 v[2:3], v[2:3], v[204:205]
	v_cvt_pk_bf16_f32 v150, v4, v5
	v_cvt_pk_bf16_f32 v151, v6, v7
	v_cvt_pk_bf16_f32 v152, v0, v1
	v_cvt_pk_bf16_f32 v153, v2, v3
	v_pk_fma_f32 v[138:139], v[4:5], v[4:5], v[138:139]
	global_store_dwordx4 v207, v[150:153], s[14:15] offset:256
	v_pk_fma_f32 v[138:139], v[6:7], v[6:7], v[138:139]
	v_pk_fma_f32 v[138:139], v[0:1], v[0:1], v[138:139]
	v_pk_fma_f32 v[138:139], v[2:3], v[2:3], v[138:139]
	v_add_f32_e32 v214, v138, v139
	v_add_u32_e32 v207, 0x8000, v207
	v_mov_b32_e32 v215, v214
	s_nop 1
	v_permlane16_swap_b32_e32 v214, v215
	s_nop 0
	v_add_f32_e32 v214, v214, v215
	v_mov_b32_e32 v215, v214
	s_nop 1
	v_permlane32_swap_b32_e32 v214, v215
	s_nop 0
	v_add_f32_e32 v214, v214, v215
	s_and_saveexec_b64 s[22:23], s[4:5]
	global_store_dword v210, v214, s[16:17] offset:3072
	s_mov_b64 exec, s[22:23]
	s_branch .LBB0_1009
